# v16 plus nt hints on read-once f32 input streams (x rows, sample memory, attention sample cache) and write-once memkv f32 stores
# baseline (speedup 1.0000x reference)
; #define GAS __attribute__((address_space(1)))
; __device__ __forceinline__ unsigned pk_bf16(float lo, float hi) { f32x2_t v = {lo, hi}; bf16x2_t b = __builtin_convertvector(v, bf16x2_t); return __builtin_bit_cast(unsigned, b); }
; __device__ __forceinline__ void p0_prologue(const Frame& F, const Args& a) {
;     ...
;     { const GAS f32x4* src = (const GAS f32x4*)a.in[8]; GAS u32x4* dst = (GAS u32x4*)(ws + WS_VMTS); const int n8 = 2 * DB * NMEM * D / 8;
;       for (int i = F.bx * 512 + F.tid; i < n8; i += F.G * 512) { const f32x4 x = src[2 * i], y = src[2 * i + 1]; u32x4 w; w.x = pk_bf16(x[0], x[1]); w.y = pk_bf16(x[2], x[3]); w.z = pk_bf16(y[0], y[1]); w.w = pk_bf16(y[2], y[3]); dst[i] = w; } }
;     { const GAS f32x4* src = (const GAS f32x4*)a.in[7]; GAS u32x4* dst = (GAS u32x4*)(ws + WS_KMS); const int n8 = 2 * DB * NMEM * D / 8;
;       for (int i = F.bx * 512 + F.tid; i < n8; i += F.G * 512) { const f32x4 x = src[2 * i], y = src[2 * i + 1]; u32x4 w; w.x = pk_bf16(x[0], x[1]); w.y = pk_bf16(x[2], x[3]); w.z = pk_bf16(y[0], y[1]); w.w = pk_bf16(y[2], y[3]); dst[i] = w; } }
.Lvk_loop:
	v_lshl_add_u64 v[14:15], v[6:7], 0, s[14:15]
	v_lshl_add_u64 v[16:17], v[8:9], 0, s[14:15]
	global_load_dwordx4 v[40:43], v[6:7], off nt
	global_load_dwordx4 v[44:47], v[6:7], off offset:16 nt
	global_load_dwordx4 v[48:51], v[14:15], off nt
	global_load_dwordx4 v[52:55], v[14:15], off offset:16 nt
	global_load_dwordx4 v[56:59], v[8:9], off nt
	global_load_dwordx4 v[60:63], v[8:9], off offset:16 nt
	global_load_dwordx4 v[64:67], v[16:17], off nt
	global_load_dwordx4 v[68:71], v[16:17], off offset:16 nt
	v_lshl_add_u64 v[18:19], v[10:11], 0, s[20:21]
	v_lshl_add_u64 v[20:21], v[12:13], 0, s[20:21]
	v_lshl_add_u64 v[6:7], v[14:15], 0, s[14:15]
	v_lshl_add_u64 v[8:9], v[16:17], 0, s[14:15]
	s_waitcnt vmcnt(6)
	v_cvt_pk_bf16_f32 v72, v40, v41
	v_cvt_pk_bf16_f32 v73, v42, v43
	v_cvt_pk_bf16_f32 v74, v44, v45
	v_cvt_pk_bf16_f32 v75, v46, v47
	global_store_dwordx4 v[10:11], v[72:75], off
	s_waitcnt vmcnt(5)
	v_cvt_pk_bf16_f32 v76, v48, v49
	v_cvt_pk_bf16_f32 v77, v50, v51
	v_cvt_pk_bf16_f32 v78, v52, v53
	v_cvt_pk_bf16_f32 v79, v54, v55
	global_store_dwordx4 v[18:19], v[76:79], off
	s_waitcnt vmcnt(4)
	v_cvt_pk_bf16_f32 v80, v56, v57
	v_cvt_pk_bf16_f32 v81, v58, v59
	v_cvt_pk_bf16_f32 v82, v60, v61
	v_cvt_pk_bf16_f32 v83, v62, v63
	global_store_dwordx4 v[12:13], v[80:83], off
	s_waitcnt vmcnt(3)
	v_cvt_pk_bf16_f32 v84, v64, v65
	v_cvt_pk_bf16_f32 v85, v66, v67
	v_cvt_pk_bf16_f32 v86, v68, v69
	v_cvt_pk_bf16_f32 v87, v70, v71
	global_store_dwordx4 v[20:21], v[84:87], off
	v_lshl_add_u64 v[10:11], v[18:19], 0, s[20:21]
	v_lshl_add_u64 v[12:13], v[20:21], 0, s[20:21]
	s_sub_i32 s22, s22, 1
	s_cmp_lg_u32 s22, 0
	s_cbranch_scc1 .Lvk_loop
	s_branch .LBB0_62

; #define GAS __attribute__((address_space(1)))
; __device__ __forceinline__ unsigned pk_bf16(float lo, float hi) { f32x2_t v = {lo, hi}; bf16x2_t b = __builtin_convertvector(v, bf16x2_t); return __builtin_bit_cast(unsigned, b); }
; __device__ __forceinline__ void norm_row(const float* xrow, const float* g, bf16_t* hb, float* xc, float* fo, int lane) {
;     const GAS f32x4* xr = (const GAS f32x4*)xrow + lane; const GAS f32x4* gr = (const GAS f32x4*)g + lane;
;     f32x4 v[4]; float s = 0.f;
; #pragma unroll
;     for (int j = 0; j < 4; ++j) { v[j] = xr[64 * j]; s += (v[j].x * v[j].x + v[j].y * v[j].y) + (v[j].z * v[j].z + v[j].w * v[j].w); }
;     if (xc) {
; #pragma unroll
;         for (int j = 0; j < 4; ++j) ((GAS f32x4*)xc + lane)[64 * j] = v[j];
;     }
;     const float rstd = 1.0f / sqrtf(wave_sum(s, lane) * (1.f / D) + RMS_EPS);
; #pragma unroll
;     for (int j = 0; j < 4; ++j) { v[j] = v[j] * rstd * gr[64 * j]; }
;     if (hb) { GAS u32x2* o8 = (GAS u32x2*)hb + lane;
; #pragma unroll
;         for (int j = 0; j < 4; ++j) { u32x2 w; w.x = pk_bf16(v[j].x, v[j].y); w.y = pk_bf16(v[j].z, v[j].w); o8[64 * j] = w; } }
; __device__ __forceinline__ void p0_prologue(const Frame& F, const Args& a) {
;     ...
;     for (int m = F.gw; m < 2 * NB * NMEM; m += F.NGW) { const int l = m / (NB * NMEM), r = m % (NB * NMEM);
;         norm_row(a.in[2] + (size_t)r * D, a.in[11] + l * D, (bf16_t*)(ws + WS_MN) + (size_t)m * D, nullptr, nullptr, F.lane); }
.LBB0_64:
	s_ashr_i32 s7, s6, 31
	s_lshr_b32 s4, s7, 20
	s_add_i32 s9, s6, s4
	s_and_b32 s4, s9, 0xfffff000
	s_sub_i32 s4, s6, s4
	s_ashr_i32 s5, s4, 31
	s_lshl_b64 s[4:5], s[4:5], 12
	v_lshl_add_u64 v[36:37], v[2:3], 0, s[4:5]
	global_load_dwordx4 v[16:19], v[36:37], off nt
	global_load_dwordx4 v[20:23], v[36:37], off offset:1024 nt
	global_load_dwordx4 v[24:27], v[36:37], off offset:3072 nt
	global_load_dwordx4 v[28:31], v[36:37], off offset:2048 nt
	s_ashr_i32 s4, s9, 12
	s_lshl_b32 s4, s4, 10
	s_ashr_i32 s5, s4, 31
	v_lshl_add_u64 v[52:53], s[4:5], 2, v[4:5]
	global_load_dwordx4 v[36:39], v[52:53], off offset:3072 nt
	s_lshl_b64 s[4:5], s[6:7], 11
	s_add_i32 s6, s6, s2
	s_cmpk_gt_i32 s6, 0x1fff
	s_waitcnt vmcnt(4)
	v_pk_mul_f32 v[40:41], v[18:19], v[18:19]
	v_pk_mul_f32 v[42:43], v[16:17], v[16:17]
	s_waitcnt vmcnt(3)
	v_pk_mul_f32 v[44:45], v[22:23], v[22:23]
	v_pk_mul_f32 v[46:47], v[20:21], v[20:21]
	v_pk_mov_b32 v[54:55], v[42:43], v[40:41] op_sel:[1,0]
	v_mov_b32_e32 v43, v41
	v_pk_mov_b32 v[40:41], v[46:47], v[44:45] op_sel:[1,0]
	v_mov_b32_e32 v47, v45
	s_waitcnt vmcnt(2)
	v_mul_f32_e32 v51, v26, v26
	s_waitcnt vmcnt(1)
	v_mul_f32_e32 v48, v29, v29
	v_mul_f32_e32 v50, v31, v31
	v_pk_add_f32 v[42:43], v[54:55], v[42:43]
	v_pk_add_f32 v[40:41], v[40:41], v[46:47]
	v_mul_f32_e32 v15, v24, v24
	v_mul_f32_e32 v33, v25, v25
	v_mul_f32_e32 v56, v27, v27
	v_pk_fma_f32 v[44:45], v[28:29], v[28:29], v[48:49] op_sel_hi:[1,1,0]
	v_pk_fma_f32 v[48:49], v[30:31], v[30:31], v[50:51] op_sel_hi:[1,1,0]
	v_pk_add_f32 v[42:43], v[42:43], v[42:43] op_sel:[0,1] op_sel_hi:[1,0]
	v_pk_add_f32 v[40:41], v[40:41], v[40:41] op_sel:[0,1] op_sel_hi:[1,0]
	v_mov_b32_e32 v45, v51
	v_mov_b32_e32 v49, v56
	v_mov_b32_e32 v43, v15
	v_mov_b32_e32 v41, v33
	v_pk_add_f32 v[44:45], v[44:45], v[48:49]
	v_pk_add_f32 v[40:41], v[42:43], v[40:41]
	s_nop 0
	v_pk_add_f32 v[40:41], v[40:41], v[44:45]
	s_nop 0
	v_add_f32_e32 v15, v40, v41
	global_load_dwordx4 v[40:43], v[52:53], off offset:2048 nt
	global_load_dwordx4 v[44:47], v[52:53], off offset:1024 nt
	global_load_dwordx4 v[48:51], v[52:53], off nt
	ds_bpermute_b32 v33, v1, v15
	v_lshl_add_u64 v[52:53], v[6:7], 0, s[4:5]
	s_waitcnt lgkmcnt(0)
	v_add_f32_e32 v15, v15, v33
	ds_bpermute_b32 v33, v8, v15
	s_waitcnt lgkmcnt(0)
	v_add_f32_e32 v15, v15, v33
	ds_bpermute_b32 v33, v9, v15
	s_waitcnt lgkmcnt(0)
	v_add_f32_e32 v15, v15, v33
	ds_bpermute_b32 v33, v10, v15
	s_waitcnt lgkmcnt(0)
	v_add_f32_e32 v15, v15, v33
	ds_bpermute_b32 v33, v11, v15
	s_waitcnt lgkmcnt(0)
	v_add_f32_e32 v15, v15, v33
	ds_bpermute_b32 v33, v12, v15
	s_waitcnt lgkmcnt(0)
	v_add_f32_e32 v15, v15, v33
	v_fmamk_f32 v15, v15, 0x3a800000, v13
	v_mul_f32_e32 v33, 0x4f800000, v15
	v_cmp_gt_f32_e32 vcc, s8, v15
	s_nop 1
	v_cndmask_b32_e32 v15, v15, v33, vcc
	v_sqrt_f32_e32 v33, v15
	s_nop 0
	v_add_u32_e32 v54, -1, v33
	v_add_u32_e32 v55, 1, v33
	v_fma_f32 v56, -v54, v33, v15
	v_fma_f32 v57, -v55, v33, v15
	v_cmp_ge_f32_e64 s[4:5], 0, v56
	s_nop 1
	v_cndmask_b32_e64 v33, v33, v54, s[4:5]
	v_cmp_lt_f32_e64 s[4:5], 0, v57
	s_nop 1
	v_cndmask_b32_e64 v33, v33, v55, s[4:5]
	v_mul_f32_e32 v54, 0x37800000, v33
	v_cndmask_b32_e32 v33, v33, v54, vcc
	v_cmp_class_f32_e32 vcc, v15, v14
	s_nop 1
	v_cndmask_b32_e32 v15, v33, v15, vcc
	v_div_scale_f32 v33, s[4:5], v15, v15, 1.0
	v_rcp_f32_e32 v54, v33
	v_div_scale_f32 v55, vcc, 1.0, v15, 1.0
	v_fma_f32 v56, -v33, v54, 1.0
	v_fmac_f32_e32 v54, v56, v54
	v_mul_f32_e32 v56, v55, v54
	v_fma_f32 v57, -v33, v56, v55
	v_fmac_f32_e32 v56, v57, v54
	v_fma_f32 v33, -v33, v56, v55
	v_div_fmas_f32 v33, v33, v54, v56
	v_div_fixup_f32 v54, v33, v15, 1.0
	v_pk_mul_f32 v[16:17], v[16:17], v[54:55] op_sel_hi:[1,0]
	v_pk_mul_f32 v[18:19], v[18:19], v[54:55] op_sel_hi:[1,0]
	v_pk_mul_f32 v[24:25], v[24:25], v[54:55] op_sel_hi:[1,0]
	v_pk_mul_f32 v[26:27], v[26:27], v[54:55] op_sel_hi:[1,0]
	v_pk_mul_f32 v[28:29], v[28:29], v[54:55] op_sel_hi:[1,0]
	v_pk_mul_f32 v[30:31], v[30:31], v[54:55] op_sel_hi:[1,0]
	v_pk_mul_f32 v[20:21], v[20:21], v[54:55] op_sel_hi:[1,0]
	v_pk_mul_f32 v[22:23], v[22:23], v[54:55] op_sel_hi:[1,0]
	s_waitcnt vmcnt(0)
	v_pk_mul_f32 v[18:19], v[50:51], v[18:19]
	v_pk_mul_f32 v[16:17], v[48:49], v[16:17]
	v_pk_mul_f32 v[26:27], v[38:39], v[26:27]
	v_pk_mul_f32 v[24:25], v[36:37], v[24:25]
	v_pk_mul_f32 v[30:31], v[42:43], v[30:31]
	v_pk_mul_f32 v[28:29], v[40:41], v[28:29]
	v_pk_mul_f32 v[22:23], v[46:47], v[22:23]
	v_pk_mul_f32 v[20:21], v[44:45], v[20:21]
	v_cvt_pk_bf16_f32 v16, v16, v17
	v_cvt_pk_bf16_f32 v17, v18, v19
	v_cvt_pk_bf16_f32 v18, v20, v21
	v_cvt_pk_bf16_f32 v19, v22, v23
	v_cvt_pk_bf16_f32 v20, v28, v29
	v_cvt_pk_bf16_f32 v21, v30, v31
	v_cvt_pk_bf16_f32 v22, v24, v25
	v_cvt_pk_bf16_f32 v23, v26, v27
	global_store_dwordx2 v[52:53], v[16:17], off
	global_store_dwordx2 v[52:53], v[18:19], off offset:512
	global_store_dwordx2 v[52:53], v[20:21], off offset:1024
	global_store_dwordx2 v[52:53], v[22:23], off offset:1536
	s_cbranch_scc0 .LBB0_64

; __device__ __forceinline__ unsigned pk_bf16(float lo, float hi) { f32x2_t v = {lo, hi}; bf16x2_t b = __builtin_convertvector(v, bf16x2_t); return __builtin_bit_cast(unsigned, b); }
;     __device__ __forceinline__ void operator()(EPI_ARGS) const {
;         const int row0 = u.row0 + wr * 64 + fr, col0 = u.col0 + wc * 32 + 8 * fq;
; #pragma unroll
;         for (int ai = 0; ai < 2; ++ai)
; #pragma unroll
;             for (int m = 0; m < 4; ++m) { const size_t off = (size_t)(row0 + ai * HALF + m * 16) * D + col0;
; #pragma unroll
;                 for (int bj = 0; bj < 2; ++bj) { const f32x4 v0 = acc[ai][bj][m][0], v1 = acc[ai][bj][m][1];
;                     *(f32x4*)(F + off + bj * HALF) = v0; *(f32x4*)(F + off + bj * HALF + 4) = v1;
;                     u32x4 w; w.x = pk_bf16(v0[0], v0[1]); w.y = pk_bf16(v0[2], v0[3]); w.z = pk_bf16(v1[0], v1[1]); w.w = pk_bf16(v1[2], v1[3]);
;                     *(u32x4*)(B + off + bj * HALF) = w; } }
;     }
.LBB0_226:
	s_mov_b32 s38, -1
	s_andn2_b64 vcc, exec, s[30:31]
	v_mbcnt_lo_u32_b32 v145, s38, 0
	v_mbcnt_hi_u32_b32 v145, s38, v145
	v_and_b32_e32 v146, 15, v145
	s_add_i32 s38, s68, s59
	v_lshrrev_b32_e32 v145, 1, v145
	v_add_u32_e32 v146, s38, v146
	s_add_i32 s38, s67, s60
	v_and_b32_e32 v145, 56, v145
	v_add_u32_e32 v148, s38, v145
	v_ashrrev_i32_e32 v147, 31, v146
	v_ashrrev_i32_e32 v149, 31, v148
	v_lshlrev_b64 v[146:147], 10, v[146:147]
	v_lshl_add_u64 v[146:147], v[146:147], 0, v[148:149]
	v_lshl_add_u64 v[148:149], v[146:147], 2, s[4:5]
	global_store_dwordx4 v[148:149], v[124:127], off nt
	global_store_dwordx4 v[148:149], v[120:123], off offset:16 nt
	s_mov_b64 s[30:31], -1
	v_cvt_pk_bf16_f32 v124, v124, v125
	v_cvt_pk_bf16_f32 v125, v126, v127
	v_cvt_pk_bf16_f32 v126, v120, v121
	v_cvt_pk_bf16_f32 v127, v122, v123
	v_lshl_add_u64 v[120:121], v[146:147], 1, s[6:7]
	global_store_dwordx4 v[120:121], v[124:127], off
	global_store_dwordx4 v[148:149], v[108:111], off offset:512 nt
	global_store_dwordx4 v[148:149], v[104:107], off offset:528 nt
	s_nop 0
	v_cvt_pk_bf16_f32 v108, v108, v109
	v_cvt_pk_bf16_f32 v109, v110, v111
	v_cvt_pk_bf16_f32 v110, v104, v105
	v_cvt_pk_bf16_f32 v111, v106, v107
	global_store_dwordx4 v[120:121], v[108:111], off offset:256
	v_cvt_pk_bf16_f32 v104, v116, v117
	v_cvt_pk_bf16_f32 v105, v118, v119
	v_lshl_add_u64 v[108:109], v[146:147], 0, s[16:17]
	v_lshl_add_u64 v[110:111], v[108:109], 2, s[4:5]
	v_cvt_pk_bf16_f32 v106, v112, v113
	v_cvt_pk_bf16_f32 v107, v114, v115
	v_lshl_add_u64 v[108:109], v[108:109], 1, s[6:7]
	global_store_dwordx4 v[110:111], v[116:119], off nt
	global_store_dwordx4 v[110:111], v[112:115], off offset:16 nt
	global_store_dwordx4 v[108:109], v[104:107], off
	global_store_dwordx4 v[110:111], v[92:95], off offset:512 nt
	global_store_dwordx4 v[110:111], v[88:91], off offset:528 nt
	s_nop 0
	v_cvt_pk_bf16_f32 v92, v92, v93
	v_cvt_pk_bf16_f32 v93, v94, v95
	v_cvt_pk_bf16_f32 v94, v88, v89
	v_cvt_pk_bf16_f32 v95, v90, v91
	global_store_dwordx4 v[108:109], v[92:95], off offset:256
	v_cvt_pk_bf16_f32 v88, v100, v101
	v_cvt_pk_bf16_f32 v89, v102, v103
	v_lshl_add_u64 v[92:93], v[146:147], 0, s[18:19]
	v_lshl_add_u64 v[94:95], v[92:93], 2, s[4:5]
	v_cvt_pk_bf16_f32 v90, v96, v97
	v_cvt_pk_bf16_f32 v91, v98, v99
	v_lshl_add_u64 v[92:93], v[92:93], 1, s[6:7]
	global_store_dwordx4 v[94:95], v[100:103], off nt
	global_store_dwordx4 v[94:95], v[96:99], off offset:16 nt
	global_store_dwordx4 v[92:93], v[88:91], off
	global_store_dwordx4 v[94:95], v[76:79], off offset:512 nt
	global_store_dwordx4 v[94:95], v[72:75], off offset:528 nt
	s_nop 0
	v_cvt_pk_bf16_f32 v76, v76, v77
	v_cvt_pk_bf16_f32 v77, v78, v79
	v_cvt_pk_bf16_f32 v78, v72, v73
	v_cvt_pk_bf16_f32 v79, v74, v75
	global_store_dwordx4 v[92:93], v[76:79], off offset:256
	v_cvt_pk_bf16_f32 v72, v84, v85
	v_cvt_pk_bf16_f32 v73, v86, v87
	v_lshl_add_u64 v[76:77], v[146:147], 0, s[20:21]
	v_lshl_add_u64 v[78:79], v[76:77], 2, s[4:5]
	v_cvt_pk_bf16_f32 v74, v80, v81
	v_cvt_pk_bf16_f32 v75, v82, v83
	v_lshl_add_u64 v[76:77], v[76:77], 1, s[6:7]
	global_store_dwordx4 v[78:79], v[84:87], off nt
	global_store_dwordx4 v[78:79], v[80:83], off offset:16 nt
	global_store_dwordx4 v[76:77], v[72:75], off
	global_store_dwordx4 v[78:79], v[68:71], off offset:512 nt
	global_store_dwordx4 v[78:79], v[64:67], off offset:528 nt
	s_nop 0
	v_cvt_pk_bf16_f32 v68, v68, v69
	v_cvt_pk_bf16_f32 v69, v70, v71
	v_cvt_pk_bf16_f32 v70, v64, v65
	v_lshl_add_u64 v[64:65], v[146:147], 0, s[22:23]
	v_cvt_pk_bf16_f32 v71, v66, v67
	v_lshl_add_u64 v[66:67], v[64:65], 2, s[4:5]
	global_store_dwordx4 v[76:77], v[68:71], off offset:256
	global_store_dwordx4 v[66:67], v[60:63], off nt
	global_store_dwordx4 v[66:67], v[56:59], off offset:16 nt
	s_nop 0
	v_cvt_pk_bf16_f32 v60, v60, v61
	v_cvt_pk_bf16_f32 v61, v62, v63
	v_cvt_pk_bf16_f32 v62, v56, v57
	v_cvt_pk_bf16_f32 v63, v58, v59
	v_lshl_add_u64 v[56:57], v[64:65], 1, s[6:7]
	global_store_dwordx4 v[56:57], v[60:63], off
	global_store_dwordx4 v[66:67], v[44:47], off offset:512 nt
	global_store_dwordx4 v[66:67], v[40:43], off offset:528 nt
	s_nop 0
	v_cvt_pk_bf16_f32 v44, v44, v45
	v_cvt_pk_bf16_f32 v45, v46, v47
	v_cvt_pk_bf16_f32 v46, v40, v41
	v_cvt_pk_bf16_f32 v47, v42, v43
	global_store_dwordx4 v[56:57], v[44:47], off offset:256
	v_cvt_pk_bf16_f32 v40, v52, v53
	v_cvt_pk_bf16_f32 v41, v54, v55
	v_lshl_add_u64 v[44:45], v[146:147], 0, s[24:25]
	v_lshl_add_u64 v[46:47], v[44:45], 2, s[4:5]
	v_cvt_pk_bf16_f32 v42, v48, v49
	v_cvt_pk_bf16_f32 v43, v50, v51
	v_lshl_add_u64 v[44:45], v[44:45], 1, s[6:7]
	global_store_dwordx4 v[46:47], v[52:55], off nt
	global_store_dwordx4 v[46:47], v[48:51], off offset:16 nt
	global_store_dwordx4 v[44:45], v[40:43], off
	global_store_dwordx4 v[46:47], v[28:31], off offset:512 nt
	global_store_dwordx4 v[46:47], v[24:27], off offset:528 nt
	s_nop 0
	v_cvt_pk_bf16_f32 v28, v28, v29
	v_cvt_pk_bf16_f32 v29, v30, v31
	v_cvt_pk_bf16_f32 v30, v24, v25
	v_cvt_pk_bf16_f32 v31, v26, v27
	global_store_dwordx4 v[44:45], v[28:31], off offset:256
	v_cvt_pk_bf16_f32 v24, v36, v37
	v_cvt_pk_bf16_f32 v25, v38, v39
	v_lshl_add_u64 v[28:29], v[146:147], 0, s[26:27]
	v_lshl_add_u64 v[30:31], v[28:29], 2, s[4:5]
	v_cvt_pk_bf16_f32 v26, v32, v33
	v_cvt_pk_bf16_f32 v27, v34, v35
	v_lshl_add_u64 v[28:29], v[28:29], 1, s[6:7]
	global_store_dwordx4 v[30:31], v[36:39], off nt
	global_store_dwordx4 v[30:31], v[32:35], off offset:16 nt
	global_store_dwordx4 v[28:29], v[24:27], off
	global_store_dwordx4 v[30:31], v[12:15], off offset:512 nt
	global_store_dwordx4 v[30:31], v[8:11], off offset:528 nt
	s_nop 0
	v_cvt_pk_bf16_f32 v12, v12, v13
	v_cvt_pk_bf16_f32 v13, v14, v15
	v_cvt_pk_bf16_f32 v14, v8, v9
	v_cvt_pk_bf16_f32 v15, v10, v11
	global_store_dwordx4 v[28:29], v[12:15], off offset:256
	v_cvt_pk_bf16_f32 v8, v20, v21
	v_cvt_pk_bf16_f32 v9, v22, v23
	v_lshl_add_u64 v[12:13], v[146:147], 0, s[28:29]
	v_lshl_add_u64 v[14:15], v[12:13], 2, s[4:5]
	v_cvt_pk_bf16_f32 v10, v16, v17
	v_cvt_pk_bf16_f32 v11, v18, v19
	v_lshl_add_u64 v[12:13], v[12:13], 1, s[6:7]
	global_store_dwordx4 v[14:15], v[20:23], off nt
	global_store_dwordx4 v[14:15], v[16:19], off offset:16 nt
	global_store_dwordx4 v[12:13], v[8:11], off
	global_store_dwordx4 v[14:15], v[4:7], off offset:512 nt
	global_store_dwordx4 v[14:15], v[0:3], off offset:528 nt
	s_nop 0
	v_cvt_pk_bf16_f32 v4, v4, v5
	v_cvt_pk_bf16_f32 v5, v6, v7
	v_cvt_pk_bf16_f32 v6, v0, v1
	v_cvt_pk_bf16_f32 v7, v2, v3
	global_store_dwordx4 v[12:13], v[4:7], off offset:256
	s_cbranch_vccnz .LBB0_215
	s_andn2_b64 vcc, exec, s[0:1]
	s_cbranch_vccnz .LBB0_214
	s_barrier
	s_branch .LBB0_214

; __device__ __forceinline__ unsigned pk_bf16(float lo, float hi) { f32x2_t v = {lo, hi}; bf16x2_t b = __builtin_convertvector(v, bf16x2_t); return __builtin_bit_cast(unsigned, b); }
;     __device__ __forceinline__ void operator()(EPI_ARGS) const {
;         const int row0 = u.row0 + wr * 64 + fr, col0 = u.col0 + wc * 32 + 8 * fq;
; #pragma unroll
;         for (int ai = 0; ai < 2; ++ai)
; #pragma unroll
;             for (int m = 0; m < 4; ++m) { const size_t off = (size_t)(row0 + ai * HALF + m * 16) * D + col0;
; #pragma unroll
;                 for (int bj = 0; bj < 2; ++bj) { const f32x4 v0 = acc[ai][bj][m][0], v1 = acc[ai][bj][m][1];
;                     *(f32x4*)(F + off + bj * HALF) = v0; *(f32x4*)(F + off + bj * HALF + 4) = v1;
;                     u32x4 w; w.x = pk_bf16(v0[0], v0[1]); w.y = pk_bf16(v0[2], v0[3]); w.z = pk_bf16(v1[0], v1[1]); w.w = pk_bf16(v1[2], v1[3]);
;                     *(u32x4*)(B + off + bj * HALF) = w; } }
;     }
.LBB0_246:
	s_mov_b32 s36, -1
	s_andn2_b64 vcc, exec, s[28:29]
	v_mbcnt_lo_u32_b32 v144, s36, 0
	v_mbcnt_hi_u32_b32 v145, s36, v144
	v_and_b32_e32 v144, 15, v145
	s_add_i32 s36, s61, s0
	v_lshrrev_b32_e32 v145, 1, v145
	v_add_u32_e32 v144, s36, v144
	s_add_i32 s36, s60, s53
	v_and_b32_e32 v145, 56, v145
	v_add_u32_e32 v146, s36, v145
	v_ashrrev_i32_e32 v145, 31, v144
	v_ashrrev_i32_e32 v147, 31, v146
	v_lshlrev_b64 v[144:145], 10, v[144:145]
	v_lshl_add_u64 v[144:145], v[144:145], 0, v[146:147]
	v_lshl_add_u64 v[146:147], v[144:145], 2, s[6:7]
	global_store_dwordx4 v[146:147], v[124:127], off nt
	global_store_dwordx4 v[146:147], v[120:123], off offset:16 nt
	s_mov_b64 s[28:29], -1
	v_cvt_pk_bf16_f32 v124, v124, v125
	v_cvt_pk_bf16_f32 v125, v126, v127
	v_cvt_pk_bf16_f32 v126, v120, v121
	v_cvt_pk_bf16_f32 v127, v122, v123
	v_lshl_add_u64 v[120:121], v[144:145], 1, s[8:9]
	global_store_dwordx4 v[120:121], v[124:127], off
	global_store_dwordx4 v[146:147], v[108:111], off offset:512 nt
	global_store_dwordx4 v[146:147], v[104:107], off offset:528 nt
	s_nop 0
	v_cvt_pk_bf16_f32 v108, v108, v109
	v_cvt_pk_bf16_f32 v109, v110, v111
	v_cvt_pk_bf16_f32 v110, v104, v105
	v_cvt_pk_bf16_f32 v111, v106, v107
	global_store_dwordx4 v[120:121], v[108:111], off offset:256
	v_cvt_pk_bf16_f32 v104, v116, v117
	v_cvt_pk_bf16_f32 v105, v118, v119
	v_lshl_add_u64 v[108:109], v[144:145], 0, s[14:15]
	v_lshl_add_u64 v[110:111], v[108:109], 2, s[6:7]
	v_cvt_pk_bf16_f32 v106, v112, v113
	v_cvt_pk_bf16_f32 v107, v114, v115
	v_lshl_add_u64 v[108:109], v[108:109], 1, s[8:9]
	global_store_dwordx4 v[110:111], v[116:119], off nt
	global_store_dwordx4 v[110:111], v[112:115], off offset:16 nt
	global_store_dwordx4 v[108:109], v[104:107], off
	global_store_dwordx4 v[110:111], v[92:95], off offset:512 nt
	global_store_dwordx4 v[110:111], v[88:91], off offset:528 nt
	s_nop 0
	v_cvt_pk_bf16_f32 v92, v92, v93
	v_cvt_pk_bf16_f32 v93, v94, v95
	v_cvt_pk_bf16_f32 v94, v88, v89
	v_cvt_pk_bf16_f32 v95, v90, v91
	global_store_dwordx4 v[108:109], v[92:95], off offset:256
	v_cvt_pk_bf16_f32 v88, v100, v101
	v_cvt_pk_bf16_f32 v89, v102, v103
	v_lshl_add_u64 v[92:93], v[144:145], 0, s[16:17]
	v_lshl_add_u64 v[94:95], v[92:93], 2, s[6:7]
	v_cvt_pk_bf16_f32 v90, v96, v97
	v_cvt_pk_bf16_f32 v91, v98, v99
	v_lshl_add_u64 v[92:93], v[92:93], 1, s[8:9]
	global_store_dwordx4 v[94:95], v[100:103], off nt
	global_store_dwordx4 v[94:95], v[96:99], off offset:16 nt
	global_store_dwordx4 v[92:93], v[88:91], off
	global_store_dwordx4 v[94:95], v[76:79], off offset:512 nt
	global_store_dwordx4 v[94:95], v[72:75], off offset:528 nt
	s_nop 0
	v_cvt_pk_bf16_f32 v76, v76, v77
	v_cvt_pk_bf16_f32 v77, v78, v79
	v_cvt_pk_bf16_f32 v78, v72, v73
	v_cvt_pk_bf16_f32 v79, v74, v75
	global_store_dwordx4 v[92:93], v[76:79], off offset:256
	v_cvt_pk_bf16_f32 v72, v84, v85
	v_cvt_pk_bf16_f32 v73, v86, v87
	v_lshl_add_u64 v[76:77], v[144:145], 0, s[18:19]
	v_lshl_add_u64 v[78:79], v[76:77], 2, s[6:7]
	v_cvt_pk_bf16_f32 v74, v80, v81
	v_cvt_pk_bf16_f32 v75, v82, v83
	v_lshl_add_u64 v[76:77], v[76:77], 1, s[8:9]
	global_store_dwordx4 v[78:79], v[84:87], off nt
	global_store_dwordx4 v[78:79], v[80:83], off offset:16 nt
	global_store_dwordx4 v[76:77], v[72:75], off
	global_store_dwordx4 v[78:79], v[68:71], off offset:512 nt
	global_store_dwordx4 v[78:79], v[64:67], off offset:528 nt
	s_nop 0
	v_cvt_pk_bf16_f32 v68, v68, v69
	v_cvt_pk_bf16_f32 v69, v70, v71
	v_cvt_pk_bf16_f32 v70, v64, v65
	v_lshl_add_u64 v[64:65], v[144:145], 0, s[20:21]
	v_cvt_pk_bf16_f32 v71, v66, v67
	v_lshl_add_u64 v[66:67], v[64:65], 2, s[6:7]
	global_store_dwordx4 v[76:77], v[68:71], off offset:256
	global_store_dwordx4 v[66:67], v[60:63], off nt
	global_store_dwordx4 v[66:67], v[56:59], off offset:16 nt
	s_nop 0
	v_cvt_pk_bf16_f32 v60, v60, v61
	v_cvt_pk_bf16_f32 v61, v62, v63
	v_cvt_pk_bf16_f32 v62, v56, v57
	v_cvt_pk_bf16_f32 v63, v58, v59
	v_lshl_add_u64 v[56:57], v[64:65], 1, s[8:9]
	global_store_dwordx4 v[56:57], v[60:63], off
	global_store_dwordx4 v[66:67], v[44:47], off offset:512 nt
	global_store_dwordx4 v[66:67], v[40:43], off offset:528 nt
	s_nop 0
	v_cvt_pk_bf16_f32 v44, v44, v45
	v_cvt_pk_bf16_f32 v45, v46, v47
	v_cvt_pk_bf16_f32 v46, v40, v41
	v_cvt_pk_bf16_f32 v47, v42, v43
	global_store_dwordx4 v[56:57], v[44:47], off offset:256
	v_cvt_pk_bf16_f32 v40, v52, v53
	v_cvt_pk_bf16_f32 v41, v54, v55
	v_lshl_add_u64 v[44:45], v[144:145], 0, s[22:23]
	v_lshl_add_u64 v[46:47], v[44:45], 2, s[6:7]
	v_cvt_pk_bf16_f32 v42, v48, v49
	v_cvt_pk_bf16_f32 v43, v50, v51
	v_lshl_add_u64 v[44:45], v[44:45], 1, s[8:9]
	global_store_dwordx4 v[46:47], v[52:55], off nt
	global_store_dwordx4 v[46:47], v[48:51], off offset:16 nt
	global_store_dwordx4 v[44:45], v[40:43], off
	global_store_dwordx4 v[46:47], v[28:31], off offset:512 nt
	global_store_dwordx4 v[46:47], v[24:27], off offset:528 nt
	s_nop 0
	v_cvt_pk_bf16_f32 v28, v28, v29
	v_cvt_pk_bf16_f32 v29, v30, v31
	v_cvt_pk_bf16_f32 v30, v24, v25
	v_cvt_pk_bf16_f32 v31, v26, v27
	global_store_dwordx4 v[44:45], v[28:31], off offset:256
	v_cvt_pk_bf16_f32 v24, v36, v37
	v_cvt_pk_bf16_f32 v25, v38, v39
	v_lshl_add_u64 v[28:29], v[144:145], 0, s[24:25]
	v_lshl_add_u64 v[30:31], v[28:29], 2, s[6:7]
	v_cvt_pk_bf16_f32 v26, v32, v33
	v_cvt_pk_bf16_f32 v27, v34, v35
	v_lshl_add_u64 v[28:29], v[28:29], 1, s[8:9]
	global_store_dwordx4 v[30:31], v[36:39], off nt
	global_store_dwordx4 v[30:31], v[32:35], off offset:16 nt
	global_store_dwordx4 v[28:29], v[24:27], off
	global_store_dwordx4 v[30:31], v[12:15], off offset:512 nt
	global_store_dwordx4 v[30:31], v[8:11], off offset:528 nt
	s_nop 0
	v_cvt_pk_bf16_f32 v12, v12, v13
	v_cvt_pk_bf16_f32 v13, v14, v15
	v_cvt_pk_bf16_f32 v14, v8, v9
	v_cvt_pk_bf16_f32 v15, v10, v11
	global_store_dwordx4 v[28:29], v[12:15], off offset:256
	v_cvt_pk_bf16_f32 v8, v20, v21
	v_cvt_pk_bf16_f32 v9, v22, v23
	v_lshl_add_u64 v[12:13], v[144:145], 0, s[26:27]
	v_lshl_add_u64 v[14:15], v[12:13], 2, s[6:7]
	v_cvt_pk_bf16_f32 v10, v16, v17
	v_cvt_pk_bf16_f32 v11, v18, v19
	v_lshl_add_u64 v[12:13], v[12:13], 1, s[8:9]
	global_store_dwordx4 v[14:15], v[20:23], off nt
	global_store_dwordx4 v[14:15], v[16:19], off offset:16 nt
	global_store_dwordx4 v[12:13], v[8:11], off
	global_store_dwordx4 v[14:15], v[4:7], off offset:512 nt
	global_store_dwordx4 v[14:15], v[0:3], off offset:528 nt
	s_nop 0
	v_cvt_pk_bf16_f32 v4, v4, v5
	v_cvt_pk_bf16_f32 v5, v6, v7
	v_cvt_pk_bf16_f32 v6, v0, v1
	v_cvt_pk_bf16_f32 v7, v2, v3
	global_store_dwordx4 v[12:13], v[4:7], off offset:256
	s_cbranch_vccnz .LBB0_235
	s_andn2_b64 vcc, exec, s[4:5]
	s_cbranch_vccnz .LBB0_234
	s_barrier
	s_branch .LBB0_234

; #define GAS __attribute__((address_space(1)))
; #define LAS __attribute__((address_space(3)))
; __device__ __forceinline__ bf16x8 cvt8(const f32x4 a, const f32x4 b) { u32x4 w; w.x = pk_bf16(a[0], a[1]); w.y = pk_bf16(a[2], a[3]); w.z = pk_bf16(b[0], b[1]); w.w = pk_bf16(b[2], b[3]); return __builtin_bit_cast(bf16x8, w); }
; __device__ __forceinline__ void load_f32(const float* Kt, const float* Vt, LAS char* vimg, int lane) {
;     const int c = lane & 7;
;     LAS char* vdst = vimg + (c >> 2) * VDH + (lane >> 3) * 64 + (c & 3) * 16; LAS char* kdst = vimg + KIMG + (lane >> 3) * KROW + c * 16;
;     const unsigned vvo = (unsigned)((lane >> 3) * D + 8 * c) * 4u;
; #pragma unroll
;     for (int hv = 0; hv < 2; ++hv) {
; #pragma unroll
;         for (int it = 4 * hv; it < 4 * hv + 4; ++it) { const GAS f32x4* p = (const GAS f32x4*)((const GAS char*)Vt + (size_t)it * 8 * D * 4 + vvo); *(LAS u32x4*)(vdst + it * 512) = __builtin_bit_cast(u32x4, cvt8(p[0], p[1])); }
;         asm volatile("" ::: "memory"); }
; #pragma unroll
;     for (int hv = 0; hv < 2; ++hv) {
; #pragma unroll
;         for (int it = 4 * hv; it < 4 * hv + 4; ++it) { const GAS f32x4* p = (const GAS f32x4*)((const GAS char*)Kt + (size_t)it * 8 * D * 4 + vvo); *(LAS u32x4*)(kdst + it * 8 * KROW) = __builtin_bit_cast(u32x4, cvt8(p[0], p[1])); }
;         asm volatile("" ::: "memory"); }
; }
; __device__ __forceinline__ void unit(int id, const Tensors& T, LAS char* vimg, int lane) {
;     ...
;             if (__all(carry > EXIT_T)) break;
;             load_f32(cKh + (size_t)kt * 64 * D, cVh + (size_t)kt * 64 * D, vimg, lane);
;             tile_step<false>(kr, vr, qr, o, carry, false, false, 64, vimg, lane, nullptr, nullptr, false);
.LBB0_368:
	v_lshl_add_u64 v[84:85], s[6:7], 0, v[150:151]
	v_add_co_u32_e32 v40, vcc, s53, v84
	v_lshl_add_u64 v[44:45], v[84:85], 0, s[16:17]
	s_nop 0
	v_addc_co_u32_e32 v41, vcc, 0, v85, vcc
	v_add_co_u32_e32 v48, vcc, s57, v84
	global_load_dwordx4 v[32:35], v[84:85], off offset:16 nt
	global_load_dwordx4 v[36:39], v[84:85], off nt
	v_addc_co_u32_e32 v49, vcc, 0, v85, vcc
	global_load_dwordx4 v[40:43], v[40:41], off nt
	s_nop 0
	global_load_dwordx4 v[44:47], v[44:45], off offset:16 nt
	v_lshl_add_u64 v[52:53], v[84:85], 0, s[10:11]
	v_add_co_u32_e32 v56, vcc, s59, v84
	global_load_dwordx4 v[48:51], v[48:49], off nt
	s_nop 0
	global_load_dwordx4 v[52:55], v[52:53], off offset:16 nt
	v_addc_co_u32_e32 v57, vcc, 0, v85, vcc
	v_lshl_add_u64 v[60:61], v[84:85], 0, s[18:19]
	global_load_dwordx4 v[56:59], v[56:57], off nt
	v_add_co_u32_e32 v92, vcc, s64, v84
	global_load_dwordx4 v[60:63], v[60:61], off offset:16 nt
	s_nop 0
	v_addc_co_u32_e32 v93, vcc, 0, v85, vcc
	v_add_co_u32_e32 v94, vcc, s65, v84
	v_lshl_add_u64 v[86:87], v[84:85], 0, s[20:21]
	s_nop 0
	v_addc_co_u32_e32 v95, vcc, 0, v85, vcc
	v_add_co_u32_e32 v96, vcc, s66, v84
	v_lshl_add_u64 v[88:89], v[84:85], 0, s[22:23]
	s_nop 0
	v_addc_co_u32_e32 v97, vcc, 0, v85, vcc
	v_lshl_add_u64 v[90:91], v[84:85], 0, s[24:25]
	s_add_u32 s6, s6, 0xfffc0000
	s_addc_u32 s7, s7, -1
	v_add_co_u32_e64 v81, s[34:35], 1, v81
	s_waitcnt vmcnt(6)
	v_cvt_pk_bf16_f32 v36, v36, v37
	v_cvt_pk_bf16_f32 v37, v38, v39
	v_cvt_pk_bf16_f32 v38, v32, v33
	v_cvt_pk_bf16_f32 v39, v34, v35
	s_waitcnt vmcnt(5)
	v_cvt_pk_bf16_f32 v32, v40, v41
	v_cvt_pk_bf16_f32 v33, v42, v43
	s_waitcnt vmcnt(4)
	v_cvt_pk_bf16_f32 v34, v44, v45
	v_cvt_pk_bf16_f32 v35, v46, v47
	ds_write_b128 v215, v[32:35] offset:512
	s_waitcnt vmcnt(3)
	v_cvt_pk_bf16_f32 v32, v48, v49
	v_cvt_pk_bf16_f32 v33, v50, v51
	s_waitcnt vmcnt(2)
	v_cvt_pk_bf16_f32 v34, v52, v53
	v_cvt_pk_bf16_f32 v35, v54, v55
	ds_write_b128 v215, v[32:35] offset:1024
	s_waitcnt vmcnt(1)
	v_cvt_pk_bf16_f32 v32, v56, v57
	v_cvt_pk_bf16_f32 v33, v58, v59
	s_waitcnt vmcnt(0)
	v_cvt_pk_bf16_f32 v34, v60, v61
	v_cvt_pk_bf16_f32 v35, v62, v63
	ds_write_b128 v215, v[36:39]
	ds_write_b128 v215, v[32:35] offset:1536
	v_add_co_u32_e32 v56, vcc, s67, v84
	global_load_dwordx4 v[32:35], v[92:93], off nt
	global_load_dwordx4 v[36:39], v[86:87], off offset:16 nt
	global_load_dwordx4 v[40:43], v[94:95], off nt
	v_addc_co_u32_e32 v57, vcc, 0, v85, vcc
	v_lshl_add_u64 v[60:61], v[84:85], 0, s[26:27]
	global_load_dwordx4 v[44:47], v[88:89], off offset:16 nt
	global_load_dwordx4 v[48:51], v[96:97], off nt
	global_load_dwordx4 v[52:55], v[90:91], off offset:16 nt
	v_lshl_add_u64 v[84:85], s[30:31], 0, v[150:151]
	global_load_dwordx4 v[56:59], v[56:57], off nt
	v_add_co_u32_e32 v88, vcc, s53, v84
	global_load_dwordx4 v[60:63], v[60:61], off offset:16 nt
	s_nop 0
	v_addc_co_u32_e32 v89, vcc, 0, v85, vcc
	v_lshl_add_u64 v[86:87], v[84:85], 0, s[16:17]
	v_lshl_add_u64 v[90:91], v[84:85], 0, s[10:11]
	v_lshl_add_u64 v[94:95], v[84:85], 0, s[24:25]
	s_add_u32 s30, s30, 0xfffc0000
	s_addc_u32 s31, s31, -1
	s_waitcnt vmcnt(7)
	v_cvt_pk_bf16_f32 v32, v32, v33
	v_cvt_pk_bf16_f32 v33, v34, v35
	s_waitcnt vmcnt(6)
	v_cvt_pk_bf16_f32 v34, v36, v37
	v_cvt_pk_bf16_f32 v35, v38, v39
	s_waitcnt vmcnt(5)
	v_cvt_pk_bf16_f32 v36, v40, v41
	s_waitcnt vmcnt(3)
	v_cvt_pk_bf16_f32 v40, v48, v49
	v_add_co_u32_e32 v48, vcc, s57, v84
	v_cvt_pk_bf16_f32 v37, v42, v43
	v_cvt_pk_bf16_f32 v38, v44, v45
	v_cvt_pk_bf16_f32 v39, v46, v47
	v_cvt_pk_bf16_f32 v41, v50, v51
	s_waitcnt vmcnt(2)
	v_cvt_pk_bf16_f32 v42, v52, v53
	v_cvt_pk_bf16_f32 v43, v54, v55
	s_waitcnt vmcnt(1)
	v_cvt_pk_bf16_f32 v44, v56, v57
	v_cvt_pk_bf16_f32 v45, v58, v59
	s_waitcnt vmcnt(0)
	v_cvt_pk_bf16_f32 v46, v60, v61
	v_cvt_pk_bf16_f32 v47, v62, v63
	ds_write_b128 v215, v[32:35] offset:2048
	ds_write_b128 v215, v[36:39] offset:2560
	ds_write_b128 v215, v[40:43] offset:3072
	ds_write_b128 v215, v[44:47] offset:3584
	v_addc_co_u32_e32 v49, vcc, 0, v85, vcc
	v_add_co_u32_e32 v56, vcc, s59, v84
	global_load_dwordx4 v[32:35], v[84:85], off offset:16 nt
	global_load_dwordx4 v[36:39], v[84:85], off nt
	v_addc_co_u32_e32 v57, vcc, 0, v85, vcc
	v_lshl_add_u64 v[60:61], v[84:85], 0, s[18:19]
	global_load_dwordx4 v[40:43], v[88:89], off nt
	global_load_dwordx4 v[44:47], v[86:87], off offset:16 nt
	s_nop 0
	global_load_dwordx4 v[48:51], v[48:49], off nt
	s_nop 0
	global_load_dwordx4 v[52:55], v[90:91], off offset:16 nt
	v_add_co_u32_e32 v88, vcc, s64, v84
	global_load_dwordx4 v[56:59], v[56:57], off nt
	s_nop 0
	v_addc_co_u32_e32 v89, vcc, 0, v85, vcc
	global_load_dwordx4 v[60:63], v[60:61], off offset:16 nt
	v_add_co_u32_e32 v92, vcc, s65, v84
	v_lshl_add_u64 v[86:87], v[84:85], 0, s[20:21]
	s_nop 0
	v_addc_co_u32_e32 v93, vcc, 0, v85, vcc
	v_lshl_add_u64 v[90:91], v[84:85], 0, s[22:23]
	s_waitcnt vmcnt(6)
	v_cvt_pk_bf16_f32 v36, v36, v37
	v_cvt_pk_bf16_f32 v37, v38, v39
	v_cvt_pk_bf16_f32 v38, v32, v33
	v_cvt_pk_bf16_f32 v39, v34, v35
	s_waitcnt vmcnt(5)
	v_cvt_pk_bf16_f32 v32, v40, v41
	s_waitcnt vmcnt(3)
	v_cvt_pk_bf16_f32 v40, v48, v49
	v_add_co_u32_e32 v48, vcc, s66, v84
	v_cvt_pk_bf16_f32 v33, v42, v43
	v_cvt_pk_bf16_f32 v34, v44, v45
	v_cvt_pk_bf16_f32 v35, v46, v47
	v_cvt_pk_bf16_f32 v41, v50, v51
	s_waitcnt vmcnt(2)
	v_cvt_pk_bf16_f32 v42, v52, v53
	v_cvt_pk_bf16_f32 v43, v54, v55
	s_waitcnt vmcnt(1)
	v_cvt_pk_bf16_f32 v44, v56, v57
	v_cvt_pk_bf16_f32 v45, v58, v59
	s_waitcnt vmcnt(0)
; __device__ __forceinline__ void load_f32(const float* Kt, const float* Vt, LAS char* vimg, int lane) {
;     ...
;     for (int hv = 0; hv < 2; ++hv) {
; #pragma unroll
;         for (int it = 4 * hv; it < 4 * hv + 4; ++it) { const GAS f32x4* p = (const GAS f32x4*)((const GAS char*)Kt + (size_t)it * 8 * D * 4 + vvo); *(LAS u32x4*)(kdst + it * 8 * KROW) = __builtin_bit_cast(u32x4, cvt8(p[0], p[1])); }
;         asm volatile("" ::: "memory"); }
; }
; __device__ __forceinline__ void load_bf16_regs(u32x4 (&kr)[8], u32x4 (&vr)[8], const bf16_t* Kt, const bf16_t* Vt, int lane) {
;     const unsigned vvo = (unsigned)((lane >> 3) * D + 8 * (lane & 7)) * 2u;
; #pragma unroll
;     for (int it = 0; it < 8; ++it) vr[it] = *(const GAS u32x4*)((const GAS char*)Vt + (size_t)it * 8 * D * 2 + vvo);
; #pragma unroll
;     for (int it = 0; it < 8; ++it) kr[it] = *(const GAS u32x4*)((const GAS char*)Kt + (size_t)it * 8 * D * 2 + vvo);
; }
; template <bool PF>
; __device__ __forceinline__ void tile_step(u32x4 (&kr)[8], u32x4 (&vr)[8], const bf16x8 (&qr)[4], f32x16 (&o)[2], float& carry, bool masked, bool upper_dead, int tq, LAS char* vimg, int lane, const bf16_t* nK, const bf16_t* nV, bool do_pf) {
;     const int hi = lane >> 5;
;     if (PF) { const int c = lane & 7; LAS char* vdst = vimg + (c >> 2) * VDH + (lane >> 3) * 64 + (c & 3) * 16; LAS char* kdst = vimg + KIMG + (lane >> 3) * KROW + c * 16;
; #pragma unroll
;         for (int it = 0; it < 8; ++it) *(LAS u32x4*)(kdst + it * 8 * KROW) = kr[it];
; #pragma unroll
;         for (int it = 0; it < 8; ++it) *(LAS u32x4*)(vdst + it * 512) = vr[it]; }
;     asm volatile("s_waitcnt lgkmcnt(0)" ::: "memory");
;     bf16x8 kf[8];
;     { LAS const char* kb = vimg + KIMG + (lane & 31) * KROW + hi * 16;
; #pragma unroll
;       for (int hf = 0; hf < 2; ++hf)
; #pragma unroll
;           for (int d0 = 0; d0 < 4; ++d0) kf[hf * 4 + d0] = *(LAS const bf16x8*)(kb + hf * 32 * KROW + d0 * 32); }
;     f32x16 p0 = {}, p1 = {};
; #pragma unroll
;     for (int d0 = 0; d0 < 4; ++d0) p0 = __builtin_amdgcn_mfma_f32_32x32x16_bf16(kf[d0], qr[d0], p0, 0, 0, 0);
;     if (!upper_dead) {
; #pragma unroll
;         for (int d0 = 0; d0 < 4; ++d0) p1 = __builtin_amdgcn_mfma_f32_32x32x16_bf16(kf[4 + d0], qr[d0], p1, 0, 0, 0);
;     }
;     if (PF && do_pf) { load_bf16_regs(kr, vr, nK, nV, lane); }
;     float k0[16], k1[16];
; #pragma unroll
	v_cvt_pk_bf16_f32 v46, v60, v61
	v_cvt_pk_bf16_f32 v47, v62, v63
	ds_write_b128 v214, v[36:39] offset:8320
	ds_write_b128 v214, v[32:35] offset:9472
	ds_write_b128 v214, v[40:43] offset:10624
	ds_write_b128 v214, v[44:47] offset:11776
	v_addc_co_u32_e32 v49, vcc, 0, v85, vcc
	v_add_co_u32_e32 v56, vcc, s67, v84
	global_load_dwordx4 v[32:35], v[88:89], off nt
	global_load_dwordx4 v[36:39], v[86:87], off offset:16 nt
	v_addc_co_u32_e32 v57, vcc, 0, v85, vcc
	v_lshl_add_u64 v[60:61], v[84:85], 0, s[26:27]
	global_load_dwordx4 v[40:43], v[92:93], off nt
	global_load_dwordx4 v[44:47], v[90:91], off offset:16 nt
	s_nop 0
	global_load_dwordx4 v[48:51], v[48:49], off nt
	s_nop 0
	global_load_dwordx4 v[52:55], v[94:95], off offset:16 nt
	s_waitcnt vmcnt(5)
	v_cvt_pk_bf16_f32 v32, v32, v33
	global_load_dwordx4 v[56:59], v[56:57], off nt
	v_cvt_pk_bf16_f32 v33, v34, v35
	global_load_dwordx4 v[60:63], v[60:61], off offset:16 nt
	s_waitcnt vmcnt(6)
	v_cvt_pk_bf16_f32 v34, v36, v37
	v_cvt_pk_bf16_f32 v35, v38, v39
	s_waitcnt vmcnt(5)
	v_cvt_pk_bf16_f32 v36, v40, v41
	v_cvt_pk_bf16_f32 v37, v42, v43
	s_waitcnt vmcnt(4)
	v_cvt_pk_bf16_f32 v38, v44, v45
	v_cvt_pk_bf16_f32 v39, v46, v47
	s_waitcnt vmcnt(3)
	v_cvt_pk_bf16_f32 v40, v48, v49
	v_cvt_pk_bf16_f32 v41, v50, v51
	s_waitcnt vmcnt(2)
	v_cvt_pk_bf16_f32 v42, v52, v53
	v_cvt_pk_bf16_f32 v43, v54, v55
	s_waitcnt vmcnt(1)
	v_cvt_pk_bf16_f32 v44, v56, v57
	v_cvt_pk_bf16_f32 v45, v58, v59
	s_waitcnt vmcnt(0)
	v_cvt_pk_bf16_f32 v46, v60, v61
	v_cvt_pk_bf16_f32 v47, v62, v63
	ds_write_b128 v214, v[32:35] offset:12928
	ds_write_b128 v214, v[36:39] offset:14080
	ds_write_b128 v214, v[40:43] offset:15232
	ds_write_b128 v214, v[44:47] offset:16384
	s_waitcnt lgkmcnt(0)
	ds_read_b128 v[32:35], v216 offset:8320
	ds_read_b128 v[84:87], v216 offset:8352
	s_waitcnt lgkmcnt(1)
	v_mfma_f32_32x32x16_bf16 v[48:63], v[32:35], v[64:67], 0
	ds_read_b128 v[32:35], v216 offset:12928
	s_waitcnt lgkmcnt(1)
	v_mfma_f32_32x32x16_bf16 v[48:63], v[84:87], v[68:71], v[48:63]
	ds_read_b128 v[84:87], v216 offset:12960
	s_waitcnt lgkmcnt(1)
	v_mfma_f32_32x32x16_bf16 v[32:47], v[32:35], v[64:67], 0
	s_waitcnt lgkmcnt(0)
	v_mfma_f32_32x32x16_bf16 v[32:47], v[84:87], v[68:71], v[32:47]
	ds_read_b128 v[84:87], v216 offset:8384
	ds_read_b128 v[88:91], v216 offset:8416
	s_waitcnt lgkmcnt(1)
	v_mfma_f32_32x32x16_bf16 v[48:63], v[84:87], v[72:75], v[48:63]
	ds_read_b128 v[84:87], v216 offset:12992
	s_waitcnt lgkmcnt(0)
	v_mfma_f32_32x32x16_bf16 v[32:47], v[84:87], v[72:75], v[32:47]
	ds_read_b128 v[84:87], v216 offset:13024
	v_mfma_f32_32x32x16_bf16 v[48:63], v[88:91], v[76:79], v[48:63]
	s_waitcnt lgkmcnt(0)
	v_mfma_f32_32x32x16_bf16 v[32:47], v[84:87], v[76:79], v[32:47]
	s_nop 9
	v_med3_f32 v48, -v48, s61, v217
	v_med3_f32 v49, -v49, s61, v217
	v_med3_f32 v83, -v50, s61, v217
	v_med3_f32 v51, -v51, s61, v217
	v_med3_f32 v52, -v52, s61, v217
	v_med3_f32 v53, -v53, s61, v217
	v_med3_f32 v54, -v54, s61, v217
	v_med3_f32 v87, -v61, s61, v217
	v_med3_f32 v89, -v62, s61, v217
	v_med3_f32 v90, -v63, s61, v217
	v_med3_f32 v32, -v32, s61, v217
	v_med3_f32 v33, -v33, s61, v217
	v_med3_f32 v34, -v34, s61, v217
	v_med3_f32 v35, -v35, s61, v217
	v_med3_f32 v36, -v36, s61, v217
	v_med3_f32 v37, -v37, s61, v217
	v_med3_f32 v38, -v38, s61, v217
	v_med3_f32 v39, -v39, s61, v217
	v_med3_f32 v40, -v40, s61, v217
	v_med3_f32 v41, -v41, s61, v217
	v_med3_f32 v99, -v42, s61, v217
	v_med3_f32 v101, -v43, s61, v217
	v_med3_f32 v86, -v60, s61, v217
	v_exp_f32_e32 v42, v48
	v_exp_f32_e32 v50, v49
	v_exp_f32_e32 v43, v83
	v_exp_f32_e32 v51, v51
	v_exp_f32_e32 v52, v52
	v_exp_f32_e32 v60, v53
	v_exp_f32_e32 v53, v54
	v_exp_f32_e32 v88, v87
	v_exp_f32_e32 v87, v89
	v_exp_f32_e32 v89, v90
	v_exp_f32_e32 v90, v32
	v_exp_f32_e32 v92, v33
	v_exp_f32_e32 v91, v34
	v_exp_f32_e32 v93, v35
	v_exp_f32_e32 v94, v36
	v_exp_f32_e32 v96, v37
	v_exp_f32_e32 v95, v38
	v_exp_f32_e32 v97, v39
	v_exp_f32_e32 v98, v40
	v_exp_f32_e32 v100, v41
	v_exp_f32_e32 v99, v99
	v_exp_f32_e32 v101, v101
	v_med3_f32 v44, -v44, s61, v217
	v_med3_f32 v45, -v45, s61, v217
	v_med3_f32 v46, -v46, s61, v217
	v_med3_f32 v47, -v47, s61, v217
	v_exp_f32_e32 v102, v44
	v_exp_f32_e32 v104, v45
	v_exp_f32_e32 v103, v46
	v_exp_f32_e32 v105, v47
	v_med3_f32 v55, -v55, s61, v217
	v_med3_f32 v56, -v56, s61, v217
	v_med3_f32 v58, -v58, s61, v217
	v_med3_f32 v59, -v59, s61, v217
	v_exp_f32_e32 v61, v55
	v_exp_f32_e32 v62, v56
	v_exp_f32_e32 v63, v58
	v_exp_f32_e32 v85, v59
	v_exp_f32_e32 v86, v86
	v_add_f32_e32 v32, 1.0, v42
	v_add_f32_e32 v33, 1.0, v50
	v_add_f32_e32 v34, 1.0, v43
	v_add_f32_e32 v35, 1.0, v51
	v_add_f32_e32 v36, 1.0, v52
	v_add_f32_e32 v45, 1.0, v53
	v_add_f32_e32 v108, 1.0, v90
	v_add_f32_e32 v109, 1.0, v92
	v_add_f32_e32 v110, 1.0, v91
	v_add_f32_e32 v111, 1.0, v93
	v_add_f32_e32 v112, 1.0, v94
	v_add_f32_e32 v113, 1.0, v96
	v_add_f32_e32 v114, 1.0, v95
	v_add_f32_e32 v115, 1.0, v97
	v_add_f32_e32 v116, 1.0, v98
	v_add_f32_e32 v117, 1.0, v100
	v_add_f32_e32 v118, 1.0, v99
	v_add_f32_e32 v119, 1.0, v101
	v_rcp_f32_e32 v38, v32
	v_rcp_f32_e32 v40, v33
	v_rcp_f32_e32 v39, v34
	v_rcp_f32_e32 v41, v35
	v_rcp_f32_e32 v44, v36
	v_rcp_f32_e32 v45, v45
	v_rcp_f32_e32 v34, v108
	v_rcp_f32_e32 v108, v109
	v_rcp_f32_e32 v35, v110
	v_rcp_f32_e32 v109, v111
	v_rcp_f32_e32 v110, v112
	v_rcp_f32_e32 v112, v113
	v_rcp_f32_e32 v111, v114
	v_rcp_f32_e32 v113, v115
	v_rcp_f32_e32 v32, v116
	v_rcp_f32_e32 v114, v117
	v_rcp_f32_e32 v33, v118
	v_rcp_f32_e32 v115, v119
	v_add_f32_e32 v120, 1.0, v102
	v_add_f32_e32 v121, 1.0, v104
	v_add_f32_e32 v122, 1.0, v103
	v_add_f32_e32 v123, 1.0, v105
	v_med3_f32 v57, -v57, s61, v217
; __device__ __forceinline__ int crow(int r, int hi) { return (r & 3) + 8 * (r >> 2) + 4 * hi; }
; template <bool PF>
; __device__ __forceinline__ void tile_step(u32x4 (&kr)[8], u32x4 (&vr)[8], const bf16x8 (&qr)[4], f32x16 (&o)[2], float& carry, bool masked, bool upper_dead, int tq, LAS char* vimg, int lane, const bf16_t* nK, const bf16_t* nV, bool do_pf) {
;     ...
;     for (int r = 0; r < 16; ++r) {
;         const float z = __builtin_amdgcn_fmed3f(p0[r], -100.f, 100.f); const float e = __builtin_amdgcn_exp2f(-z); float sg = __builtin_amdgcn_rcpf(1.f + e); float kp = e * sg;
;         if (masked && !(crow(r, hi) < tq)) { sg = 0.f; kp = 1.f; } p0[r] = sg; k0[r] = kp; }
;     if (!upper_dead) {
; #pragma unroll
;         for (int r = 0; r < 16; ++r) {
;             const float z = __builtin_amdgcn_fmed3f(p1[r], -100.f, 100.f); const float e = __builtin_amdgcn_exp2f(-z); float sg = __builtin_amdgcn_rcpf(1.f + e); float kp = e * sg;
;             if (masked && !(crow(r, hi) + 32 < tq)) { sg = 0.f; kp = 1.f; } p1[r] = sg; k1[r] = kp; }
;     } else {
; #pragma unroll
;         for (int r = 0; r < 16; ++r) { p1[r] = 0.f; k1[r] = 1.f; }
;     }
;     float Glo[8], Ghi[8];
; #pragma unroll
;     for (int a = 0; a < 8; ++a) { const float* kk = a < 4 ? k0 + 4 * a : k1 + 4 * (a - 4); const float g = (kk[0] * kk[1]) * (kk[2] * kk[3]);
;         auto rr = __builtin_amdgcn_permlane32_swap(__float_as_uint(g), __float_as_uint(g), false, false); Glo[a] = __uint_as_float(rr[0]); Ghi[a] = __uint_as_float(rr[1]); }
;     float sx = __builtin_amdgcn_exp2f(-carry);
; #pragma unroll
;     for (int a = 7; a >= 0; --a) {
;         const float base = hi == 0 ? sx * Ghi[a] : sx;
;         if (a >= 4) { const int q = 4 * (a - 4);
;             const float s3 = base, s2 = s3 * k1[q + 3], s1 = s2 * k1[q + 2], s0 = s1 * k1[q + 1];
;             p1[q + 3] *= s3; p1[q + 2] *= s2; p1[q + 1] *= s1; p1[q] *= s0;
;         } else { const int q = 4 * a;
;             const float s3 = base, s2 = s3 * k0[q + 3], s1 = s2 * k0[q + 2], s0 = s1 * k0[q + 1];
;             p0[q + 3] *= s3; p0[q + 2] *= s2; p0[q + 1] *= s1; p0[q] *= s0;
;         }
;         sx *= Glo[a] * Ghi[a];
;     }
;     carry = -__builtin_amdgcn_logf(sx);
	v_rcp_f32_e32 v116, v120
	v_rcp_f32_e32 v118, v121
	v_rcp_f32_e32 v117, v122
	v_rcp_f32_e32 v119, v123
	v_exp_f32_e32 v84, v57
	v_add_f32_e32 v37, 1.0, v60
	v_add_f32_e32 v46, 1.0, v61
	v_add_f32_e32 v47, 1.0, v62
	v_add_f32_e32 v55, 1.0, v63
	v_add_f32_e32 v56, 1.0, v85
	v_add_f32_e32 v57, 1.0, v86
	v_add_f32_e32 v58, 1.0, v88
	v_add_f32_e32 v59, 1.0, v87
	v_rcp_f32_e32 v48, v37
	v_rcp_f32_e32 v49, v46
	v_rcp_f32_e32 v36, v47
	v_rcp_f32_e32 v37, v55
	v_rcp_f32_e32 v55, v56
	v_rcp_f32_e32 v56, v57
	v_rcp_f32_e32 v106, v58
	v_rcp_f32_e32 v57, v59
	v_pk_mul_f32 v[46:47], v[42:43], v[38:39]
	v_pk_mul_f32 v[42:43], v[50:51], v[40:41]
	v_pk_mul_f32 v[58:59], v[52:53], v[44:45]
	v_pk_mul_f32 v[50:51], v[98:99], v[32:33]
	v_pk_mul_f32 v[52:53], v[100:101], v[114:115]
	v_pk_mul_f32 v[98:99], v[102:103], v[116:117]
	v_pk_mul_f32 v[128:129], v[50:51], v[52:53]
	v_pk_mul_f32 v[100:101], v[104:105], v[118:119]
	v_pk_mul_f32 v[128:129], v[128:129], v[128:129] op_sel:[0,1] op_sel_hi:[1,0]
	v_pk_mul_f32 v[130:131], v[98:99], v[100:101]
	v_exp_f32_e64 v129, -v82
	v_pk_mul_f32 v[130:131], v[130:131], v[130:131] op_sel:[0,1] op_sel_hi:[1,0]
	v_pk_mul_f32 v[102:103], v[46:47], v[42:43]
	v_mov_b32_e32 v46, v130
	s_nop 1
	v_permlane32_swap_b32_e32 v130, v46
	v_add_f32_e32 v83, 1.0, v89
	v_mul_f32_e32 v50, v129, v46
	v_rcp_f32_e32 v107, v83
	v_pk_mul_f32 v[94:95], v[94:95], v[110:111]
	v_pk_mul_f32 v[96:97], v[96:97], v[112:113]
	v_cndmask_b32_e64 v83, v129, v50, s[4:5]
	v_pk_mul_f32 v[126:127], v[94:95], v[96:97]
	v_mov_b32_e32 v132, v128
	v_mul_f32_e32 v82, v101, v83
	v_mov_b32_e32 v134, v117
	v_mov_b32_e32 v135, v119
	v_pk_mul_f32 v[126:127], v[126:127], v[126:127] op_sel:[0,1] op_sel_hi:[1,0]
	v_permlane32_swap_b32_e32 v128, v132
	v_pk_mul_f32 v[134:135], v[134:135], v[82:83]
	v_mul_f32_e32 v83, v99, v82
	v_mul_f32_e32 v133, v130, v46
	v_mov_b32_e32 v98, v126
	v_mul_f32_e32 v82, v100, v83
	v_mov_b32_e32 v100, v33
	v_mov_b32_e32 v101, v115
	v_mov_b32_e32 v33, v114
	v_pk_mul_f32 v[114:115], v[128:129], v[132:133]
	v_permlane32_swap_b32_e32 v126, v98
	v_mov_b32_e32 v127, v114
	v_mov_b32_e32 v99, v115
	v_pk_mul_f32 v[90:91], v[90:91], v[34:35]
	v_pk_mul_f32 v[92:93], v[92:93], v[108:109]
	v_mov_b32_e32 v117, v118
	v_mul_f32_e32 v46, v115, v132
	v_mov_b32_e32 v118, v111
	v_mov_b32_e32 v119, v113
	v_mov_b32_e32 v111, v112
	v_pk_mul_f32 v[112:113], v[126:127], v[98:99]
	v_pk_mul_f32 v[124:125], v[90:91], v[92:93]
	v_pk_mul_f32 v[82:83], v[116:117], v[82:83]
	v_cndmask_b32_e64 v117, v115, v46, s[4:5]
	v_mul_f32_e32 v46, v113, v98
	v_pk_mul_f32 v[124:125], v[124:125], v[124:125] op_sel:[0,1] op_sel_hi:[1,0]
	v_cndmask_b32_e64 v99, v113, v46, s[4:5]
	v_mov_b32_e32 v94, v124
	v_mul_f32_e32 v98, v97, v99
	s_nop 0
	v_permlane32_swap_b32_e32 v124, v94
	v_mul_f32_e32 v97, v95, v98
	v_mov_b32_e32 v125, v112
	v_mov_b32_e32 v95, v113
	v_pk_mul_f32 v[86:87], v[86:87], v[56:57]
	v_pk_mul_f32 v[88:89], v[88:89], v[106:107]
	v_pk_mul_f32 v[114:115], v[118:119], v[98:99]
	v_mov_b32_e32 v98, v35
	v_mov_b32_e32 v99, v109
	v_mov_b32_e32 v35, v108
	v_pk_mul_f32 v[108:109], v[124:125], v[94:95]
	v_add_f32_e32 v54, 1.0, v84
	v_pk_mul_f32 v[122:123], v[86:87], v[88:89]
	v_mul_f32_e32 v46, v109, v94
	v_rcp_f32_e32 v54, v54
	v_pk_mul_f32 v[122:123], v[122:123], v[122:123] op_sel:[0,1] op_sel_hi:[1,0]
	v_cndmask_b32_e64 v95, v109, v46, s[4:5]
	v_mov_b32_e32 v90, v122
	v_mul_f32_e32 v94, v93, v95
	s_nop 0
	v_permlane32_swap_b32_e32 v122, v90
	v_mul_f32_e32 v93, v91, v94
	v_mov_b32_e32 v123, v108
	v_mov_b32_e32 v91, v109
	v_pk_mul_f32 v[98:99], v[98:99], v[94:95]
	v_mov_b32_e32 v94, v57
	v_mov_b32_e32 v95, v107
	v_mov_b32_e32 v57, v106
	v_pk_mul_f32 v[106:107], v[122:123], v[90:91]
	v_pk_mul_f32 v[62:63], v[62:63], v[36:37]
	v_pk_mul_f32 v[84:85], v[84:85], v[54:55]
	v_mul_f32_e32 v46, v107, v90
	v_pk_mul_f32 v[120:121], v[62:63], v[84:85]
	v_cndmask_b32_e64 v91, v107, v46, s[4:5]
	v_pk_mul_f32 v[120:121], v[120:121], v[120:121] op_sel:[0,1] op_sel_hi:[1,0]
	v_mul_f32_e32 v90, v89, v91
	v_mov_b32_e32 v86, v120
	v_mul_f32_e32 v89, v87, v90
	s_nop 0
	v_permlane32_swap_b32_e32 v120, v86
	v_mul_f32_e32 v88, v88, v89
	v_mov_b32_e32 v121, v106
	v_mov_b32_e32 v87, v107
	v_pk_mul_f32 v[60:61], v[60:61], v[48:49]
	v_pk_mul_f32 v[88:89], v[56:57], v[88:89]
	v_mov_b32_e32 v56, v37
	v_mov_b32_e32 v57, v55
	v_mov_b32_e32 v37, v54
	v_pk_mul_f32 v[54:55], v[120:121], v[86:87]
	v_pk_mul_f32 v[104:105], v[58:59], v[60:61]
	v_mul_f32_e32 v46, v55, v86
	v_pk_mul_f32 v[104:105], v[104:105], v[104:105] op_sel:[0,1] op_sel_hi:[1,0]
	v_cndmask_b32_e64 v87, v55, v46, s[4:5]
	v_mov_b32_e32 v62, v104
	v_mul_f32_e32 v86, v85, v87
	s_nop 0
	v_permlane32_swap_b32_e32 v104, v62
	v_mul_f32_e32 v85, v63, v86
	v_mov_b32_e32 v105, v54
	v_mov_b32_e32 v63, v55
	v_pk_mul_f32 v[94:95], v[94:95], v[90:91]
	v_pk_mul_f32 v[90:91], v[56:57], v[86:87]
	v_mov_b32_e32 v56, v45
	v_mov_b32_e32 v57, v49
	v_mov_b32_e32 v45, v48
	v_pk_mul_f32 v[48:49], v[104:105], v[62:63]
	v_pk_mul_f32 v[102:103], v[102:103], v[102:103] op_sel:[0,1] op_sel_hi:[1,0]
	v_mul_f32_e32 v46, v49, v62
	v_cndmask_b32_e64 v55, v49, v46, s[4:5]
	v_mov_b32_e32 v58, v102
	v_mul_f32_e32 v54, v61, v55
	s_nop 0
	v_permlane32_swap_b32_e32 v102, v58
	v_pk_mul_f32 v[56:57], v[56:57], v[54:55]
	v_mul_f32_e32 v55, v59, v54
	v_mov_b32_e32 v103, v48
	v_mov_b32_e32 v59, v49
	v_mul_f32_e32 v54, v60, v55
	v_pk_mul_f32 v[60:61], v[102:103], v[58:59]
	v_pk_mul_f32 v[54:55], v[44:45], v[54:55]
	v_mov_b32_e32 v44, v39
	v_mov_b32_e32 v39, v40
	v_mul_f32_e32 v40, v61, v58
	v_mov_b32_e32 v45, v41
	v_cndmask_b32_e64 v41, v61, v40, s[4:5]
	v_mul_f32_e32 v40, v43, v41
	v_pk_mul_f32 v[48:49], v[44:45], v[40:41]
	v_mul_f32_e32 v41, v47, v40
	ds_read_b64_tr_b16 v[44:45], v80
	ds_read_b64_tr_b16 v[46:47], v80 offset:512
	v_mul_f32_e32 v40, v42, v41
	v_pk_mul_f32 v[38:39], v[38:39], v[40:41]
	v_cvt_pk_bf16_f32 v40, v54, v55
	v_cvt_pk_bf16_f32 v38, v38, v39
	v_cvt_pk_bf16_f32 v39, v48, v49
	v_cvt_pk_bf16_f32 v41, v56, v57
	ds_read_b64_tr_b16 v[54:55], v80 offset:1024
	ds_read_b64_tr_b16 v[56:57], v80 offset:1536
	s_waitcnt lgkmcnt(2)
; #define LAS __attribute__((address_space(3)))
; __device__ __forceinline__ unsigned pk_bf16(float lo, float hi) { f32x2_t v = {lo, hi}; bf16x2_t b = __builtin_convertvector(v, bf16x2_t); return __builtin_bit_cast(unsigned, b); }
; __device__ __forceinline__ s16x4 vtr(LAS const char* p) { typedef short v4i16_t __attribute__((ext_vector_type(4))); return __builtin_bit_cast(s16x4, __builtin_amdgcn_ds_read_tr16_b64_v4i16((LAS v4i16_t*)p)); }
; template <bool PF>
; __device__ __forceinline__ void tile_step(u32x4 (&kr)[8], u32x4 (&vr)[8], const bf16x8 (&qr)[4], f32x16 (&o)[2], float& carry, bool masked, bool upper_dead, int tq, LAS char* vimg, int lane, const bf16_t* nK, const bf16_t* nV, bool do_pf) {
;     ...
;     bf16x8 pf[4];
; #pragma unroll
;     for (int s = 0; s < 4; ++s) { const f32x16& p = s < 2 ? p0 : p1; const int q = 8 * (s & 1);
;         u32x4 w; w.x = pk_bf16(p[q], p[q + 1]); w.y = pk_bf16(p[q + 2], p[q + 3]); w.z = pk_bf16(p[q + 4], p[q + 5]); w.w = pk_bf16(p[q + 6], p[q + 7]); pf[s] = __builtin_bit_cast(bf16x8, w); }
;     LAS const char* vb = vimg + (4 * hi + ((lane & 15) >> 2)) * 64 + ((lane >> 4) & 1) * 32 + (lane & 3) * 8;
; #pragma unroll
;     for (int dh = 0; dh < 2; ++dh) {
; #pragma unroll
;         for (int s = 0; s < 2; ++s) { const s16x4 lo = vtr(vb + dh * VDH + s * 1024), hh = vtr(vb + dh * VDH + s * 1024 + 512);
;             const bf16x8 vf = (bf16x8){lo[0], lo[1], lo[2], lo[3], hh[0], hh[1], hh[2], hh[3]};
;             o[dh] = __builtin_amdgcn_mfma_f32_32x32x16_bf16(vf, pf[s], o[dh], 0, 0, 0); }
;         if (!upper_dead) {
; #pragma unroll
;             for (int s = 2; s < 4; ++s) { const s16x4 lo = vtr(vb + dh * VDH + s * 1024), hh = vtr(vb + dh * VDH + s * 1024 + 512);
;                 const bf16x8 vf = (bf16x8){lo[0], lo[1], lo[2], lo[3], hh[0], hh[1], hh[2], hh[3]};
;                 o[dh] = __builtin_amdgcn_mfma_f32_32x32x16_bf16(vf, pf[s], o[dh], 0, 0, 0); }
;         }
;     }
;     asm volatile("s_waitcnt lgkmcnt(0)" ::: "memory");
	v_mfma_f32_32x32x16_bf16 v[0:15], v[44:47], v[38:41], v[0:15]
	v_mul_f32_e32 v84, v84, v85
	v_mul_f32_e64 v36, v36, v84
	v_mul_f32_e64 v37, v37, v85
	v_cvt_pk_bf16_f32 v43, v90, v91
	v_cvt_pk_bf16_f32 v42, v36, v37
	v_cvt_pk_bf16_f32 v44, v88, v89
	v_cvt_pk_bf16_f32 v45, v94, v95
	ds_read_b64_tr_b16 v[46:47], v80 offset:2048
	ds_read_b64_tr_b16 v[48:49], v80 offset:2560
	s_waitcnt lgkmcnt(2)
	v_mfma_f32_32x32x16_bf16 v[0:15], v[54:57], v[42:45], v[0:15]
	v_mul_f32_e32 v96, v96, v97
	v_mul_f32_e32 v92, v92, v93
	v_mul_f32_e64 v96, v110, v96
	v_mul_f32_e64 v97, v111, v97
	v_mul_f32_e64 v34, v34, v92
	v_mul_f32_e64 v35, v35, v93
	v_cvt_pk_bf16_f32 v36, v96, v97
	v_cvt_pk_bf16_f32 v34, v34, v35
	v_cvt_pk_bf16_f32 v35, v98, v99
	v_cvt_pk_bf16_f32 v37, v114, v115
	v_mul_f32_e32 v116, v53, v117
	ds_read_b64_tr_b16 v[54:55], v80 offset:3072
	ds_read_b64_tr_b16 v[56:57], v80 offset:3584
	s_waitcnt lgkmcnt(2)
	v_mfma_f32_32x32x16_bf16 v[0:15], v[46:49], v[34:37], v[0:15]
	v_mul_f32_e32 v47, v51, v116
	v_mul_f32_e32 v46, v52, v47
	v_mul_f32_e64 v100, v100, v116
	v_mul_f32_e64 v101, v101, v117
	v_mul_f32_e64 v32, v32, v46
	v_mul_f32_e64 v33, v33, v47
	v_cvt_pk_bf16_f32 v47, v100, v101
	v_cvt_pk_bf16_f32 v46, v32, v33
	v_cvt_pk_bf16_f32 v48, v82, v83
	v_cvt_pk_bf16_f32 v49, v134, v135
	v_mul_f32_e32 v32, v60, v61
	v_log_f32_e32 v32, v32
	s_waitcnt lgkmcnt(0)
	v_mfma_f32_32x32x16_bf16 v[0:15], v[54:57], v[46:49], v[0:15]
	ds_read_b64_tr_b16 v[50:51], v80 offset:4160
	ds_read_b64_tr_b16 v[52:53], v80 offset:4672
	ds_read_b64_tr_b16 v[54:55], v80 offset:5184
	ds_read_b64_tr_b16 v[56:57], v80 offset:5696
	v_xor_b32_e32 v82, 0x80000000, v32
	s_waitcnt lgkmcnt(2)
	v_mfma_f32_32x32x16_bf16 v[16:31], v[50:53], v[38:41], v[16:31]
	s_waitcnt lgkmcnt(0)
	v_mfma_f32_32x32x16_bf16 v[16:31], v[54:57], v[42:45], v[16:31]
	ds_read_b64_tr_b16 v[38:39], v80 offset:6208
	ds_read_b64_tr_b16 v[40:41], v80 offset:6720
	ds_read_b64_tr_b16 v[42:43], v80 offset:7232
	ds_read_b64_tr_b16 v[44:45], v80 offset:7744
	s_waitcnt lgkmcnt(0)
	s_waitcnt lgkmcnt(2)
	v_mfma_f32_32x32x16_bf16 v[16:31], v[38:41], v[34:37], v[16:31]
	s_waitcnt lgkmcnt(0)
	v_mfma_f32_32x32x16_bf16 v[16:31], v[42:45], v[46:49], v[16:31]
	s_andn2_b64 vcc, exec, s[34:35]
	s_cbranch_vccz .LBB0_316

; __device__ __forceinline__ unsigned pk_bf16(float lo, float hi) { f32x2_t v = {lo, hi}; bf16x2_t b = __builtin_convertvector(v, bf16x2_t); return __builtin_bit_cast(unsigned, b); }
;     __device__ __forceinline__ void operator()(EPI_ARGS) const {
;         const int row0 = u.row0 + wr * 64 + fr, col0 = u.col0 + wc * 32 + 8 * fq;
; #pragma unroll
;         for (int ai = 0; ai < 2; ++ai)
; #pragma unroll
;             for (int m = 0; m < 4; ++m) { const size_t off = (size_t)(row0 + ai * HALF + m * 16) * D + col0;
; #pragma unroll
;                 for (int bj = 0; bj < 2; ++bj) { const f32x4 v0 = acc[ai][bj][m][0], v1 = acc[ai][bj][m][1];
;                     *(f32x4*)(F + off + bj * HALF) = v0; *(f32x4*)(F + off + bj * HALF + 4) = v1;
;                     u32x4 w; w.x = pk_bf16(v0[0], v0[1]); w.y = pk_bf16(v0[2], v0[3]); w.z = pk_bf16(v1[0], v1[1]); w.w = pk_bf16(v1[2], v1[3]);
;                     *(u32x4*)(B + off + bj * HALF) = w; } }
;     }
.LBB0_1056:
	s_mov_b32 s20, -1
	s_andn2_b64 vcc, exec, s[14:15]
	v_mbcnt_lo_u32_b32 v141, s20, 0
	v_mbcnt_hi_u32_b32 v141, s20, v141
	v_and_b32_e32 v142, 15, v141
	s_add_i32 s20, s51, s43
	v_lshrrev_b32_e32 v141, 1, v141
	v_add_u32_e32 v142, s20, v142
	s_add_i32 s20, s50, s44
	v_and_b32_e32 v141, 56, v141
	v_add_u32_e32 v144, s20, v141
	v_ashrrev_i32_e32 v143, 31, v142
	v_ashrrev_i32_e32 v145, 31, v144
	v_lshlrev_b64 v[142:143], 10, v[142:143]
	v_lshl_add_u64 v[142:143], v[142:143], 0, v[144:145]
	v_lshl_add_u64 v[144:145], v[142:143], 2, s[4:5]
	global_store_dwordx4 v[144:145], v[124:127], off nt
	global_store_dwordx4 v[144:145], v[120:123], off offset:16 nt
	s_mov_b64 s[20:21], 0x4000
	v_cvt_pk_bf16_f32 v124, v124, v125
	v_cvt_pk_bf16_f32 v125, v126, v127
	v_cvt_pk_bf16_f32 v126, v120, v121
	v_cvt_pk_bf16_f32 v127, v122, v123
	v_lshl_add_u64 v[120:121], v[142:143], 1, s[10:11]
	global_store_dwordx4 v[120:121], v[124:127], off
	global_store_dwordx4 v[144:145], v[108:111], off offset:512 nt
	global_store_dwordx4 v[144:145], v[104:107], off offset:528 nt
	s_mov_b64 s[14:15], -1
	v_cvt_pk_bf16_f32 v108, v108, v109
	v_cvt_pk_bf16_f32 v109, v110, v111
	v_cvt_pk_bf16_f32 v110, v104, v105
	v_cvt_pk_bf16_f32 v111, v106, v107
	global_store_dwordx4 v[120:121], v[108:111], off offset:256
	v_cvt_pk_bf16_f32 v104, v116, v117
	v_cvt_pk_bf16_f32 v105, v118, v119
	v_lshl_add_u64 v[108:109], v[142:143], 0, s[20:21]
	v_lshl_add_u64 v[110:111], v[108:109], 2, s[4:5]
	v_cvt_pk_bf16_f32 v106, v112, v113
	v_cvt_pk_bf16_f32 v107, v114, v115
	v_lshl_add_u64 v[108:109], v[108:109], 1, s[10:11]
	global_store_dwordx4 v[110:111], v[116:119], off nt
	global_store_dwordx4 v[110:111], v[112:115], off offset:16 nt
	global_store_dwordx4 v[108:109], v[104:107], off
	global_store_dwordx4 v[110:111], v[92:95], off offset:512 nt
	global_store_dwordx4 v[110:111], v[88:91], off offset:528 nt
	s_mov_b64 s[20:21], 0x8000
	v_cvt_pk_bf16_f32 v92, v92, v93
	v_cvt_pk_bf16_f32 v93, v94, v95
	v_cvt_pk_bf16_f32 v94, v88, v89
	v_cvt_pk_bf16_f32 v95, v90, v91
	global_store_dwordx4 v[108:109], v[92:95], off offset:256
	v_cvt_pk_bf16_f32 v88, v100, v101
	v_cvt_pk_bf16_f32 v89, v102, v103
	v_lshl_add_u64 v[92:93], v[142:143], 0, s[20:21]
	v_lshl_add_u64 v[94:95], v[92:93], 2, s[4:5]
	v_cvt_pk_bf16_f32 v90, v96, v97
	v_cvt_pk_bf16_f32 v91, v98, v99
	v_lshl_add_u64 v[92:93], v[92:93], 1, s[10:11]
	global_store_dwordx4 v[94:95], v[100:103], off nt
	global_store_dwordx4 v[94:95], v[96:99], off offset:16 nt
	global_store_dwordx4 v[92:93], v[88:91], off
	global_store_dwordx4 v[94:95], v[76:79], off offset:512 nt
	global_store_dwordx4 v[94:95], v[72:75], off offset:528 nt
	s_mov_b64 s[20:21], 0xc000
	v_cvt_pk_bf16_f32 v76, v76, v77
	v_cvt_pk_bf16_f32 v77, v78, v79
	v_cvt_pk_bf16_f32 v78, v72, v73
	v_cvt_pk_bf16_f32 v79, v74, v75
	global_store_dwordx4 v[92:93], v[76:79], off offset:256
	v_cvt_pk_bf16_f32 v72, v84, v85
	v_cvt_pk_bf16_f32 v73, v86, v87
	v_lshl_add_u64 v[76:77], v[142:143], 0, s[20:21]
	v_lshl_add_u64 v[78:79], v[76:77], 2, s[4:5]
	v_cvt_pk_bf16_f32 v74, v80, v81
	v_cvt_pk_bf16_f32 v75, v82, v83
	v_lshl_add_u64 v[76:77], v[76:77], 1, s[10:11]
	s_mov_b64 s[20:21], 0x20000
	global_store_dwordx4 v[78:79], v[84:87], off nt
	global_store_dwordx4 v[78:79], v[80:83], off offset:16 nt
	global_store_dwordx4 v[76:77], v[72:75], off
	global_store_dwordx4 v[78:79], v[68:71], off offset:512 nt
	global_store_dwordx4 v[78:79], v[64:67], off offset:528 nt
	s_nop 0
	v_cvt_pk_bf16_f32 v68, v68, v69
	v_cvt_pk_bf16_f32 v69, v70, v71
	v_cvt_pk_bf16_f32 v70, v64, v65
	v_lshl_add_u64 v[64:65], v[142:143], 0, s[20:21]
	v_cvt_pk_bf16_f32 v71, v66, v67
	v_lshl_add_u64 v[66:67], v[64:65], 2, s[4:5]
	global_store_dwordx4 v[76:77], v[68:71], off offset:256
	global_store_dwordx4 v[66:67], v[60:63], off nt
	global_store_dwordx4 v[66:67], v[56:59], off offset:16 nt
	s_mov_b64 s[20:21], 0x24000
	v_cvt_pk_bf16_f32 v60, v60, v61
	v_cvt_pk_bf16_f32 v61, v62, v63
	v_cvt_pk_bf16_f32 v62, v56, v57
	v_cvt_pk_bf16_f32 v63, v58, v59
	v_lshl_add_u64 v[56:57], v[64:65], 1, s[10:11]
	global_store_dwordx4 v[56:57], v[60:63], off
	global_store_dwordx4 v[66:67], v[44:47], off offset:512 nt
	global_store_dwordx4 v[66:67], v[40:43], off offset:528 nt
	s_nop 0
	v_cvt_pk_bf16_f32 v44, v44, v45
	v_cvt_pk_bf16_f32 v45, v46, v47
	v_cvt_pk_bf16_f32 v46, v40, v41
	v_cvt_pk_bf16_f32 v47, v42, v43
	global_store_dwordx4 v[56:57], v[44:47], off offset:256
	v_cvt_pk_bf16_f32 v40, v52, v53
	v_cvt_pk_bf16_f32 v41, v54, v55
	v_lshl_add_u64 v[44:45], v[142:143], 0, s[20:21]
	v_lshl_add_u64 v[46:47], v[44:45], 2, s[4:5]
	v_cvt_pk_bf16_f32 v42, v48, v49
	v_cvt_pk_bf16_f32 v43, v50, v51
	v_lshl_add_u64 v[44:45], v[44:45], 1, s[10:11]
	global_store_dwordx4 v[46:47], v[52:55], off nt
	global_store_dwordx4 v[46:47], v[48:51], off offset:16 nt
	global_store_dwordx4 v[44:45], v[40:43], off
	global_store_dwordx4 v[46:47], v[28:31], off offset:512 nt
	global_store_dwordx4 v[46:47], v[24:27], off offset:528 nt
	s_mov_b64 s[20:21], 0x28000
	v_cvt_pk_bf16_f32 v28, v28, v29
	v_cvt_pk_bf16_f32 v29, v30, v31
	v_cvt_pk_bf16_f32 v30, v24, v25
	v_cvt_pk_bf16_f32 v31, v26, v27
	global_store_dwordx4 v[44:45], v[28:31], off offset:256
	v_cvt_pk_bf16_f32 v24, v36, v37
	v_cvt_pk_bf16_f32 v25, v38, v39
	v_lshl_add_u64 v[28:29], v[142:143], 0, s[20:21]
	v_lshl_add_u64 v[30:31], v[28:29], 2, s[4:5]
	v_cvt_pk_bf16_f32 v26, v32, v33
	v_cvt_pk_bf16_f32 v27, v34, v35
	v_lshl_add_u64 v[28:29], v[28:29], 1, s[10:11]
	global_store_dwordx4 v[30:31], v[36:39], off nt
	global_store_dwordx4 v[30:31], v[32:35], off offset:16 nt
	global_store_dwordx4 v[28:29], v[24:27], off
	global_store_dwordx4 v[30:31], v[12:15], off offset:512 nt
	global_store_dwordx4 v[30:31], v[8:11], off offset:528 nt
	s_mov_b64 s[20:21], 0x2c000
	v_cvt_pk_bf16_f32 v12, v12, v13
	v_cvt_pk_bf16_f32 v13, v14, v15
	v_cvt_pk_bf16_f32 v14, v8, v9
	v_cvt_pk_bf16_f32 v15, v10, v11
	global_store_dwordx4 v[28:29], v[12:15], off offset:256
	v_cvt_pk_bf16_f32 v8, v20, v21
	v_cvt_pk_bf16_f32 v9, v22, v23
	v_lshl_add_u64 v[12:13], v[142:143], 0, s[20:21]
	v_lshl_add_u64 v[14:15], v[12:13], 2, s[4:5]
	v_cvt_pk_bf16_f32 v10, v16, v17
	v_cvt_pk_bf16_f32 v11, v18, v19
	v_lshl_add_u64 v[12:13], v[12:13], 1, s[10:11]
	global_store_dwordx4 v[14:15], v[20:23], off nt
	global_store_dwordx4 v[14:15], v[16:19], off offset:16 nt
	global_store_dwordx4 v[12:13], v[8:11], off
	global_store_dwordx4 v[14:15], v[4:7], off offset:512 nt
	global_store_dwordx4 v[14:15], v[0:3], off offset:528 nt
	s_nop 0
	v_cvt_pk_bf16_f32 v4, v4, v5
	v_cvt_pk_bf16_f32 v5, v6, v7
	v_cvt_pk_bf16_f32 v6, v0, v1
	v_cvt_pk_bf16_f32 v7, v2, v3
	global_store_dwordx4 v[12:13], v[4:7], off offset:256
	s_cbranch_vccnz .LBB0_1045
	s_andn2_b64 vcc, exec, s[2:3]
	s_cbranch_vccnz .LBB0_1044
	s_barrier
	s_branch .LBB0_1044

; __device__ __forceinline__ unsigned pk_bf16(float lo, float hi) { f32x2_t v = {lo, hi}; bf16x2_t b = __builtin_convertvector(v, bf16x2_t); return __builtin_bit_cast(unsigned, b); }
;     __device__ __forceinline__ void operator()(EPI_ARGS) const {
;         const int row0 = u.row0 + wr * 64 + fr, col0 = u.col0 + wc * 32 + 8 * fq;
; #pragma unroll
;         for (int ai = 0; ai < 2; ++ai)
; #pragma unroll
;             for (int m = 0; m < 4; ++m) { const size_t off = (size_t)(row0 + ai * HALF + m * 16) * D + col0;
; #pragma unroll
;                 for (int bj = 0; bj < 2; ++bj) { const f32x4 v0 = acc[ai][bj][m][0], v1 = acc[ai][bj][m][1];
;                     *(f32x4*)(F + off + bj * HALF) = v0; *(f32x4*)(F + off + bj * HALF + 4) = v1;
;                     u32x4 w; w.x = pk_bf16(v0[0], v0[1]); w.y = pk_bf16(v0[2], v0[3]); w.z = pk_bf16(v1[0], v1[1]); w.w = pk_bf16(v1[2], v1[3]);
;                     *(u32x4*)(B + off + bj * HALF) = w; } }
;     }
.LBB0_1076:
	s_mov_b32 s16, -1
	s_andn2_b64 vcc, exec, s[10:11]
	v_mbcnt_lo_u32_b32 v140, s16, 0
	v_mbcnt_hi_u32_b32 v141, s16, v140
	v_and_b32_e32 v140, 15, v141
	s_add_i32 s16, s44, s36
	v_lshrrev_b32_e32 v141, 1, v141
	v_add_u32_e32 v140, s16, v140
	s_add_i32 s16, s43, s37
	v_and_b32_e32 v141, 56, v141
	v_add_u32_e32 v142, s16, v141
	v_ashrrev_i32_e32 v141, 31, v140
	v_ashrrev_i32_e32 v143, 31, v142
	v_lshlrev_b64 v[140:141], 10, v[140:141]
	v_lshl_add_u64 v[140:141], v[140:141], 0, v[142:143]
	v_lshl_add_u64 v[142:143], v[140:141], 2, s[0:1]
	global_store_dwordx4 v[142:143], v[124:127], off nt
	global_store_dwordx4 v[142:143], v[120:123], off offset:16 nt
	s_mov_b64 s[16:17], 0x4000
	v_cvt_pk_bf16_f32 v124, v124, v125
	v_cvt_pk_bf16_f32 v125, v126, v127
	v_cvt_pk_bf16_f32 v126, v120, v121
	v_cvt_pk_bf16_f32 v127, v122, v123
	v_lshl_add_u64 v[120:121], v[140:141], 1, s[4:5]
	global_store_dwordx4 v[120:121], v[124:127], off
	global_store_dwordx4 v[142:143], v[108:111], off offset:512 nt
	global_store_dwordx4 v[142:143], v[104:107], off offset:528 nt
	s_mov_b64 s[10:11], -1
	v_cvt_pk_bf16_f32 v108, v108, v109
	v_cvt_pk_bf16_f32 v109, v110, v111
	v_cvt_pk_bf16_f32 v110, v104, v105
	v_cvt_pk_bf16_f32 v111, v106, v107
	global_store_dwordx4 v[120:121], v[108:111], off offset:256
	v_cvt_pk_bf16_f32 v104, v116, v117
	v_cvt_pk_bf16_f32 v105, v118, v119
	v_lshl_add_u64 v[108:109], v[140:141], 0, s[16:17]
	v_lshl_add_u64 v[110:111], v[108:109], 2, s[0:1]
	v_cvt_pk_bf16_f32 v106, v112, v113
	v_cvt_pk_bf16_f32 v107, v114, v115
	v_lshl_add_u64 v[108:109], v[108:109], 1, s[4:5]
	global_store_dwordx4 v[110:111], v[116:119], off nt
	global_store_dwordx4 v[110:111], v[112:115], off offset:16 nt
	global_store_dwordx4 v[108:109], v[104:107], off
	global_store_dwordx4 v[110:111], v[92:95], off offset:512 nt
	global_store_dwordx4 v[110:111], v[88:91], off offset:528 nt
	s_mov_b64 s[16:17], 0x8000
	v_cvt_pk_bf16_f32 v92, v92, v93
	v_cvt_pk_bf16_f32 v93, v94, v95
	v_cvt_pk_bf16_f32 v94, v88, v89
	v_cvt_pk_bf16_f32 v95, v90, v91
	global_store_dwordx4 v[108:109], v[92:95], off offset:256
	v_cvt_pk_bf16_f32 v88, v100, v101
	v_cvt_pk_bf16_f32 v89, v102, v103
	v_lshl_add_u64 v[92:93], v[140:141], 0, s[16:17]
	v_lshl_add_u64 v[94:95], v[92:93], 2, s[0:1]
	v_cvt_pk_bf16_f32 v90, v96, v97
	v_cvt_pk_bf16_f32 v91, v98, v99
	v_lshl_add_u64 v[92:93], v[92:93], 1, s[4:5]
	global_store_dwordx4 v[94:95], v[100:103], off nt
	global_store_dwordx4 v[94:95], v[96:99], off offset:16 nt
	global_store_dwordx4 v[92:93], v[88:91], off
	global_store_dwordx4 v[94:95], v[76:79], off offset:512 nt
	global_store_dwordx4 v[94:95], v[72:75], off offset:528 nt
	s_mov_b64 s[16:17], 0xc000
	v_cvt_pk_bf16_f32 v76, v76, v77
	v_cvt_pk_bf16_f32 v77, v78, v79
	v_cvt_pk_bf16_f32 v78, v72, v73
	v_cvt_pk_bf16_f32 v79, v74, v75
	global_store_dwordx4 v[92:93], v[76:79], off offset:256
	v_cvt_pk_bf16_f32 v72, v84, v85
	v_cvt_pk_bf16_f32 v73, v86, v87
	v_lshl_add_u64 v[76:77], v[140:141], 0, s[16:17]
	v_lshl_add_u64 v[78:79], v[76:77], 2, s[0:1]
	v_cvt_pk_bf16_f32 v74, v80, v81
	v_cvt_pk_bf16_f32 v75, v82, v83
	v_lshl_add_u64 v[76:77], v[76:77], 1, s[4:5]
	s_mov_b64 s[16:17], 0x20000
	global_store_dwordx4 v[78:79], v[84:87], off nt
	global_store_dwordx4 v[78:79], v[80:83], off offset:16 nt
	global_store_dwordx4 v[76:77], v[72:75], off
	global_store_dwordx4 v[78:79], v[68:71], off offset:512 nt
	global_store_dwordx4 v[78:79], v[64:67], off offset:528 nt
	s_nop 0
	v_cvt_pk_bf16_f32 v68, v68, v69
	v_cvt_pk_bf16_f32 v69, v70, v71
	v_cvt_pk_bf16_f32 v70, v64, v65
	v_lshl_add_u64 v[64:65], v[140:141], 0, s[16:17]
	v_cvt_pk_bf16_f32 v71, v66, v67
	v_lshl_add_u64 v[66:67], v[64:65], 2, s[0:1]
	global_store_dwordx4 v[76:77], v[68:71], off offset:256
	global_store_dwordx4 v[66:67], v[60:63], off nt
	global_store_dwordx4 v[66:67], v[56:59], off offset:16 nt
	s_mov_b64 s[16:17], 0x24000
	v_cvt_pk_bf16_f32 v60, v60, v61
	v_cvt_pk_bf16_f32 v61, v62, v63
	v_cvt_pk_bf16_f32 v62, v56, v57
	v_cvt_pk_bf16_f32 v63, v58, v59
	v_lshl_add_u64 v[56:57], v[64:65], 1, s[4:5]
	global_store_dwordx4 v[56:57], v[60:63], off
	global_store_dwordx4 v[66:67], v[44:47], off offset:512 nt
	global_store_dwordx4 v[66:67], v[40:43], off offset:528 nt
	s_nop 0
	v_cvt_pk_bf16_f32 v44, v44, v45
	v_cvt_pk_bf16_f32 v45, v46, v47
	v_cvt_pk_bf16_f32 v46, v40, v41
	v_cvt_pk_bf16_f32 v47, v42, v43
	global_store_dwordx4 v[56:57], v[44:47], off offset:256
	v_cvt_pk_bf16_f32 v40, v52, v53
	v_cvt_pk_bf16_f32 v41, v54, v55
	v_lshl_add_u64 v[44:45], v[140:141], 0, s[16:17]
	v_lshl_add_u64 v[46:47], v[44:45], 2, s[0:1]
	v_cvt_pk_bf16_f32 v42, v48, v49
	v_cvt_pk_bf16_f32 v43, v50, v51
	v_lshl_add_u64 v[44:45], v[44:45], 1, s[4:5]
	global_store_dwordx4 v[46:47], v[52:55], off nt
	global_store_dwordx4 v[46:47], v[48:51], off offset:16 nt
	global_store_dwordx4 v[44:45], v[40:43], off
	global_store_dwordx4 v[46:47], v[28:31], off offset:512 nt
	global_store_dwordx4 v[46:47], v[24:27], off offset:528 nt
	s_mov_b64 s[16:17], 0x28000
	v_cvt_pk_bf16_f32 v28, v28, v29
	v_cvt_pk_bf16_f32 v29, v30, v31
	v_cvt_pk_bf16_f32 v30, v24, v25
	v_cvt_pk_bf16_f32 v31, v26, v27
	global_store_dwordx4 v[44:45], v[28:31], off offset:256
	v_cvt_pk_bf16_f32 v24, v36, v37
	v_cvt_pk_bf16_f32 v25, v38, v39
	v_lshl_add_u64 v[28:29], v[140:141], 0, s[16:17]
	v_lshl_add_u64 v[30:31], v[28:29], 2, s[0:1]
	v_cvt_pk_bf16_f32 v26, v32, v33
	v_cvt_pk_bf16_f32 v27, v34, v35
	v_lshl_add_u64 v[28:29], v[28:29], 1, s[4:5]
	global_store_dwordx4 v[30:31], v[36:39], off nt
	global_store_dwordx4 v[30:31], v[32:35], off offset:16 nt
	global_store_dwordx4 v[28:29], v[24:27], off
	global_store_dwordx4 v[30:31], v[12:15], off offset:512 nt
	global_store_dwordx4 v[30:31], v[8:11], off offset:528 nt
	s_mov_b64 s[16:17], 0x2c000
	v_cvt_pk_bf16_f32 v12, v12, v13
	v_cvt_pk_bf16_f32 v13, v14, v15
	v_cvt_pk_bf16_f32 v14, v8, v9
	v_cvt_pk_bf16_f32 v15, v10, v11
	global_store_dwordx4 v[28:29], v[12:15], off offset:256
	v_cvt_pk_bf16_f32 v8, v20, v21
	v_cvt_pk_bf16_f32 v9, v22, v23
	v_lshl_add_u64 v[12:13], v[140:141], 0, s[16:17]
	v_lshl_add_u64 v[14:15], v[12:13], 2, s[0:1]
	v_cvt_pk_bf16_f32 v10, v16, v17
	v_cvt_pk_bf16_f32 v11, v18, v19
	v_lshl_add_u64 v[12:13], v[12:13], 1, s[4:5]
	global_store_dwordx4 v[14:15], v[20:23], off nt
	global_store_dwordx4 v[14:15], v[16:19], off offset:16 nt
	global_store_dwordx4 v[12:13], v[8:11], off
	global_store_dwordx4 v[14:15], v[4:7], off offset:512 nt
	global_store_dwordx4 v[14:15], v[0:3], off offset:528 nt
	s_nop 0
	v_cvt_pk_bf16_f32 v4, v4, v5
	v_cvt_pk_bf16_f32 v5, v6, v7
	v_cvt_pk_bf16_f32 v6, v0, v1
	v_cvt_pk_bf16_f32 v7, v2, v3
	global_store_dwordx4 v[12:13], v[4:7], off offset:256
	s_cbranch_vccnz .LBB0_1065
	s_andn2_b64 vcc, exec, s[2:3]
	s_cbranch_vccnz .LBB0_1064
	s_barrier
	s_branch .LBB0_1064
